# hand-written MLA and GQA attention loops (staggered S/softmax/PV, v_max3 trees, SGPR-base prefetch, conflict-free ds_read_b64 V frags); same numerics
# speedup vs baseline: 1.0514x; 1.0514x over previous
; DEVI unsigned pack2(float a, float b) { f32x2_t v = {a, b}; bf16x2_t r = __builtin_convertvector(v, bf16x2_t); return *reinterpret_cast<unsigned*>(&r); }
; DEVI float ex2(float x) { return __builtin_amdgcn_exp2f(x); }
; DEVI f32x4 mfma16(bf16x8 a, bf16x8 b, f32x4 c) { return __builtin_amdgcn_mfma_f32_16x16x32_bf16(a, b, c, 0, 0, 0); }
; template <int DK>
; DEVI void attn_tile(const char* kb, const char* vb, const bool first, const bf16x8 (&qf)[2][DK / 32], f32x4 (&o)[2][4],
;                     float (&mrun)[2], float (&lsum)[2], const int l15, const int quad) {
;     ...
;     float ps = 0.f;
; #pragma unroll
;     for (int ks = 0; ks < 4; ++ks)
; #pragma unroll
;       for (int j = 0; j < 4; ++j) { float pv = ex2(s[qt][ks][j]); s[qt][ks][j] = pv; ps += pv; }
;     lsum[qt] += ps;
; #pragma unroll
;     for (int k2 = 0; k2 < 2; ++k2) {
;       u32x4 wv;
;       wv[0] = pack2(s[qt][2 * k2][0], s[qt][2 * k2][1]);
;       wv[1] = pack2(s[qt][2 * k2][2], s[qt][2 * k2][3]);
;       wv[2] = pack2(s[qt][2 * k2 + 1][0], s[qt][2 * k2 + 1][1]);
;       wv[3] = pack2(s[qt][2 * k2 + 1][2], s[qt][2 * k2 + 1][3]);
;       pf[qt][k2] = as_bf8(wv);
;     }
;   }
; #pragma unroll
;   for (int dd = 0; dd < 4; ++dd)
; #pragma unroll
;     for (int k2 = 0; k2 < 2; ++k2) {
;       u32x2 lo = *reinterpret_cast<const u32x2*>(vb + (dd * 16 + l15) * 144 + (k2 * 32 + quad * 4) * 2);
;       u32x2 hi = *reinterpret_cast<const u32x2*>(vb + (dd * 16 + l15) * 144 + (k2 * 32 + 16 + quad * 4) * 2);
;       u32x4 vv = {lo[0], lo[1], hi[0], hi[1]};
;       bf16x8 vf = as_bf8(vv);
;       o[0][dd] = mfma16(vf, pf[0][k2], o[0][dd]);
;       o[1][dd] = mfma16(vf, pf[1][k2], o[1][dd]);
;     }
; template <int DK, int QP>
; DEVI void attn_item(const bf* __restrict__ Q, const bf* __restrict__ Kp, const bf* __restrict__ Vt, bf* __restrict__ outp  ,
;                     long row_base, int j0, int nkeys, char* smem) {
;     ...
;   for (int t = 0; t < nt; ++t) {
;     ALOAD(rkA, rvA, min(t + 1, nt - 1));
;     const char* kb = smem + (t & 1) * STG;
; #pragma unroll
;     for (int pr = 0; pr < QP; ++pr) {
;       attn_tile<DK>(kb, kb + KSZ, t == 0, qf[pr], o[pr], mrun[pr], lsum[pr], l15, quad);
;       if (QP > 1) __builtin_amdgcn_sched_barrier(0);
;     }
;     AWRITE(rkA, rvA, (t + 1) & 1);
;     __syncthreads();
;   }
.LBB0_613:
	v_exp_f32_e32 v96, v96
	v_exp_f32_e32 v97, v97
	v_exp_f32_e32 v98, v98
	v_exp_f32_e32 v99, v99
	v_mad_i64_i32 v[164:165], s[10:11], v116, s17, 0
	v_mad_i64_i32 v[166:167], s[10:11], v117, s17, 0
	v_add_f32_e32 v116, 0, v96
	v_exp_f32_e32 v117, v92
	v_add_f32_e32 v116, v97, v116
	v_add_f32_e32 v116, v98, v116
	v_add_f32_e32 v116, v99, v116
	v_add_f32_e32 v92, v117, v116
	v_exp_f32_e32 v116, v93
	v_exp_f32_e32 v192, v94
	v_exp_f32_e32 v193, v95
	v_exp_f32_e32 v88, v88
	v_add_f32_e32 v92, v116, v92
	v_exp_f32_e32 v89, v89
	v_add_f32_e32 v92, v192, v92
	v_exp_f32_e32 v90, v90
	v_add_f32_e32 v92, v193, v92
	v_exp_f32_e32 v91, v91
	v_add_f32_e32 v92, v88, v92
	v_exp_f32_e32 v84, v84
	v_add_f32_e32 v92, v89, v92
	v_exp_f32_e32 v85, v85
	v_add_f32_e32 v92, v90, v92
	v_exp_f32_e32 v86, v86
	v_add_f32_e32 v92, v91, v92
	v_exp_f32_e32 v87, v87
	v_add_f32_e32 v92, v84, v92
	v_add_f32_e32 v92, v85, v92
	v_add_f32_e32 v92, v86, v92
	v_add_f32_e32 v92, v87, v92
	v_add_f32_e32 v174, 0, v92
	v_add_f32_e32 v92, 0, v145
	v_add_f32_e32 v92, v146, v92
	v_add_f32_e32 v92, v147, v92
	v_add_f32_e32 v92, v168, v92
	v_add_f32_e32 v92, v169, v92
	v_add_f32_e32 v92, v170, v92
	v_add_f32_e32 v92, v171, v92
	v_add_f32_e32 v92, v175, v92
	v_add_f32_e32 v92, v176, v92
	v_add_f32_e32 v92, v177, v92
	v_add_f32_e32 v92, v204, v92
	v_add_f32_e32 v92, v205, v92
	v_add_f32_e32 v92, v206, v92
	v_add_f32_e32 v92, v207, v92
	v_add_f32_e32 v92, v208, v92
	v_add_f32_e32 v92, v209, v92
	v_add_f32_e32 v175, 0, v92
	v_add_f32_e32 v92, 0, v118
	v_add_f32_e32 v92, v119, v92
	v_add_f32_e32 v92, v120, v92
	v_add_f32_e32 v92, v121, v92
	v_add_f32_e32 v92, v122, v92
	v_add_f32_e32 v92, v123, v92
	v_add_f32_e32 v92, v135, v92
	v_add_f32_e32 v92, v136, v92
	v_add_f32_e32 v92, v137, v92
	v_add_f32_e32 v92, v138, v92
	v_add_f32_e32 v92, v139, v92
	v_add_f32_e32 v92, v140, v92
	v_exp_f32_e32 v136, v68
	v_exp_f32_e32 v137, v69
	v_exp_f32_e32 v138, v70
	v_exp_f32_e32 v139, v71
	ds_read2_b64 v[68:71], v133 offset1:4
	v_add_f32_e32 v92, v141, v92
	v_add_f32_e32 v92, v142, v92
	v_add_f32_e32 v92, v143, v92
	v_add_f32_e32 v92, v144, v92
	v_exp_f32_e32 v140, v72
	v_exp_f32_e32 v141, v73
	v_exp_f32_e32 v142, v74
	v_exp_f32_e32 v143, v75
	v_exp_f32_e32 v144, v76
	v_exp_f32_e32 v145, v77
	v_exp_f32_e32 v146, v78
	v_exp_f32_e32 v147, v79
	ds_read2_b64 v[76:79], v133 offset0:8 offset1:12
	v_cvt_pk_bf16_f32 v96, v96, v97
	v_cvt_pk_bf16_f32 v97, v98, v99
	v_cvt_pk_bf16_f32 v98, v117, v116
	v_cvt_pk_bf16_f32 v99, v192, v193
	v_exp_f32_e32 v168, v80
	v_exp_f32_e32 v169, v81
	v_exp_f32_e32 v170, v82
	v_exp_f32_e32 v171, v83
	v_cvt_pk_bf16_f32 v120, v136, v137
	v_cvt_pk_bf16_f32 v121, v138, v139
	v_cvt_pk_bf16_f32 v122, v140, v141
	v_cvt_pk_bf16_f32 v123, v142, v143
	s_waitcnt lgkmcnt(1)
	v_mfma_f32_16x16x32_bf16 v[72:75], v[68:71], v[96:99], 0
	v_add_f32_e32 v176, 0, v92
	s_movk_i32 s11, 0x90
	v_mov_b32_e32 v92, 0x1200
	v_mfma_f32_16x16x32_bf16 v[68:71], v[68:71], v[120:123], 0
	v_mad_u32_u24 v208, v148, s11, v92
	v_mov_b32_e32 v92, 0x1b00
	v_mad_u32_u24 v209, v148, s11, v92
	v_cvt_pk_bf16_f32 v92, v88, v89
	v_cvt_pk_bf16_f32 v93, v90, v91
	v_cvt_pk_bf16_f32 v94, v84, v85
	v_cvt_pk_bf16_f32 v95, v86, v87
	v_cvt_pk_bf16_f32 v116, v144, v145
	v_cvt_pk_bf16_f32 v117, v146, v147
	v_cvt_pk_bf16_f32 v118, v168, v169
	v_cvt_pk_bf16_f32 v119, v170, v171
	s_waitcnt lgkmcnt(0)
	v_mfma_f32_16x16x32_bf16 v[72:75], v[76:79], v[92:95], v[72:75]
	ds_read2_b64 v[84:87], v134 offset0:8 offset1:12
	s_add_i32 s10, s3, -1
	v_add_u32_e32 v177, 0xa00, v163
	v_mfma_f32_16x16x32_bf16 v[68:71], v[76:79], v[116:119], v[68:71]
	ds_read2_b64 v[76:79], v134 offset1:4
	v_add_u32_e32 v204, 0x1400, v163
	v_add_u32_e32 v205, 0x1e00, v163
	s_waitcnt lgkmcnt(0)
	v_mfma_f32_16x16x32_bf16 v[80:83], v[76:79], v[96:99], 0
	v_mul_u32_u24_e32 v206, 0x90, v148
	v_mad_u32_u24 v207, v148, s11, v191
	v_mfma_f32_16x16x32_bf16 v[76:79], v[76:79], v[120:123], 0
	v_mfma_f32_16x16x32_bf16 v[80:83], v[84:87], v[92:95], v[80:83]
	v_mfma_f32_16x16x32_bf16 v[76:79], v[84:87], v[116:119], v[76:79]
	ds_read2_b64 v[84:87], v132 offset1:4
	ds_read2_b64 v[132:135], v132 offset0:8 offset1:12
	s_waitcnt lgkmcnt(1)
	v_mfma_f32_16x16x32_bf16 v[88:91], v[84:87], v[96:99], 0
	v_mfma_f32_16x16x32_bf16 v[84:87], v[84:87], v[120:123], 0
	s_waitcnt lgkmcnt(0)
	v_mfma_f32_16x16x32_bf16 v[88:91], v[132:135], v[92:95], v[88:91]
	v_mfma_f32_16x16x32_bf16 v[84:87], v[132:135], v[116:119], v[84:87]
	ds_read2_b64 v[132:135], v131 offset1:4
	s_waitcnt lgkmcnt(0)
	v_mfma_f32_16x16x32_bf16 v[96:99], v[132:135], v[96:99], 0
	v_mfma_f32_16x16x32_bf16 v[120:123], v[132:135], v[120:123], 0
	ds_read2_b64 v[132:135], v131 offset0:8 offset1:12
	s_waitcnt lgkmcnt(0)
	v_mfma_f32_16x16x32_bf16 v[96:99], v[132:135], v[92:95], v[96:99]
	v_mfma_f32_16x16x32_bf16 v[92:95], v[132:135], v[116:119], v[120:123]
	s_waitcnt vmcnt(3)
	ds_write_b128 v128, v[100:103] offset:19456
	s_waitcnt vmcnt(2)
	ds_write_b128 v129, v[104:107] offset:19456
	s_waitcnt vmcnt(1)
	ds_write_b128 v130, v[108:111] offset:29696
	s_waitcnt vmcnt(0)
	ds_write_b128 v130, v[112:115] offset:34304
	v_add_f32_e32 v100, 0, v136
	v_add_f32_e32 v100, v137, v100
	v_add_f32_e32 v100, v138, v100
	v_add_f32_e32 v100, v139, v100
	v_add_f32_e32 v100, v140, v100
	v_add_f32_e32 v100, v141, v100
	v_add_f32_e32 v100, v142, v100
	v_add_f32_e32 v100, v143, v100
	v_add_f32_e32 v100, v144, v100
	v_add_f32_e32 v100, v145, v100
	v_add_f32_e32 v100, v146, v100
	v_add_f32_e32 v100, v147, v100
	v_add_f32_e32 v100, v168, v100
	v_add_f32_e32 v100, v169, v100
	v_add_f32_e32 v100, v170, v100
	v_add_f32_e32 v100, v171, v100
	v_add_f32_e32 v210, 0, v100
	s_mov_b32 s11, 1
	v_lshl_add_u64 v[168:169], v[124:125], 1, s[12:13]
	v_lshl_add_u64 v[170:171], v[126:127], 1, s[12:13]
	s_waitcnt lgkmcnt(0)
	s_barrier
	v_add_u32_e32 v168, v163, v2
	v_mul_u32_u24_e32 v169, 0x90, v148
	v_add_u32_e32 v169, v169, v162
	v_add_u32_e32 v169, 0x2800, v169
	v_add_u32_e32 v170, v1, v149
	v_add_u32_e32 v171, v151, v153
	v_add_u32_e32 v177, v158, v155
	v_lshlrev_b32_e32 v204, 4, v178
	v_and_b32_e32 v206, 7, v178
	v_lshlrev_b32_e32 v206, 4, v206
	v_add_u32_e32 v207, v206, v166
	v_add_u32_e32 v206, v206, v164
	v_readfirstlane_b32 s22, v160
	v_readfirstlane_b32 s23, v161
	v_add_u32_e32 v205, 0x1000, v204
	s_add_u32 s12, s12, 0x4000
	s_addc_u32 s13, s13, 0
	s_add_u32 s22, s22, 0x100
	s_addc_u32 s23, s23, 0
	s_mov_b32 s18, 0x4c00
	v_xor_b32_e32 v228, 0x80000000, v159
	v_mov_b32_e32 v229, v228
	v_mov_b32_e32 v230, v228
	v_mov_b32_e32 v231, v228
	v_xor_b32_e32 v236, 0x80000000, v157
	v_mov_b32_e32 v237, v236
	v_mov_b32_e32 v238, v236
	v_mov_b32_e32 v239, v236
	s_nop 4
; DEVI float ex2(float x) { return __builtin_amdgcn_exp2f(x); }
; DEVI f32x4 mfma16(bf16x8 a, bf16x8 b, f32x4 c) { return __builtin_amdgcn_mfma_f32_16x16x32_bf16(a, b, c, 0, 0, 0); }
; template <int DK>
; DEVI void attn_tile(const char* kb, const char* vb, const bool first, const bf16x8 (&qf)[2][DK / 32], f32x4 (&o)[2][4],
;                     float (&mrun)[2], float (&lsum)[2], const int l15, const int quad) {
;     ...
;   f32x4 s[2][4];
; #pragma unroll
;   for (int qt = 0; qt < 2; ++qt)
; #pragma unroll
;     for (int ks = 0; ks < 4; ++ks) { const float nm = -mrun[qt]; s[qt][ks] = f32x4{nm, nm, nm, nm}; }
; #pragma unroll
;   for (int ks = 0; ks < 4; ++ks)
; #pragma unroll
;     for (int kk = 0; kk < NKK; ++kk) {
;       bf16x8 kf = *reinterpret_cast<const bf16x8*>(kb + (ks * 16 + l15) * KSTR + (kk * 32 + quad * 8) * 2);
;       s[0][ks] = mfma16(kf, qf[0][kk], s[0][ks]);
;       s[1][ks] = mfma16(kf, qf[1][kk], s[1][ks]);
;     }
;   bf16x8 pf[2][2];
; #pragma unroll
;   for (int qt = 0; qt < 2; ++qt) {
;     float mx = fmaxf(fmaxf(s[qt][0][0], s[qt][0][1]), fmaxf(s[qt][0][2], s[qt][0][3]));
; #pragma unroll
;     for (int ks = 1; ks < 4; ++ks) mx = fmaxf(mx, fmaxf(fmaxf(s[qt][ks][0], s[qt][ks][1]), fmaxf(s[qt][ks][2], s[qt][ks][3])));
;     if (__any(first || (mx > 8.f))) {
;       float rm = fmaxf(mx, __shfl_xor(mx, 16));
;       rm = fmaxf(rm, __shfl_xor(rm, 32));
;       const float delta = first ? rm : fmaxf(rm, 0.f);
;       const float alpha = first ? 1.f : ex2(-delta);
;       mrun[qt] += delta;
;       lsum[qt] *= alpha;
; #pragma unroll
;       for (int ks = 0; ks < 4; ++ks)
; #pragma unroll
;         for (int j = 0; j < 4; ++j) s[qt][ks][j] -= delta;
; #pragma unroll
;       for (int dd = 0; dd < 4; ++dd)
; #pragma unroll
;         for (int j = 0; j < 4; ++j) o[qt][dd][j] *= alpha;
;     }
;     float ps = 0.f;
; #pragma unroll
;     for (int ks = 0; ks < 4; ++ks)
; #pragma unroll
;       for (int j = 0; j < 4; ++j) { float pv = ex2(s[qt][ks][j]); s[qt][ks][j] = pv; ps += pv; }
;     lsum[qt] += ps;
.Lgqa_loop_g:
	v_add_u32_e32 v211, s18, v168
	ds_read_b128 v[100:103], v211
	ds_read_b128 v[104:107], v211 offset:64
	global_load_dwordx4 v[192:195], v204, s[12:13]
	global_load_dwordx4 v[196:199], v205, s[12:13]
	global_load_dwordx4 v[244:247], v206, s[22:23]
	global_load_dwordx4 v[164:167], v207, s[22:23]
	s_add_i32 s96, s11, 2
	s_cmp_lt_i32 s96, s3
	s_cselect_b32 s96, 0x2000, 0
	s_cselect_b32 s17, 0x80, 0
	s_add_u32 s12, s12, s96
	s_addc_u32 s13, s13, 0
	s_add_u32 s22, s22, s17
	s_addc_u32 s23, s23, 0
	ds_read_b128 v[108:111], v211 offset:2560
	ds_read_b128 v[112:115], v211 offset:2624
	ds_read_b128 v[116:119], v211 offset:5120
	ds_read_b128 v[120:123], v211 offset:5184
	ds_read_b128 v[124:127], v211 offset:7680
	ds_read_b128 v[128:131], v211 offset:7744
	s_waitcnt lgkmcnt(7)
	v_mfma_f32_16x16x32_bf16 v[132:135], v[100:103], v[4:7], v[228:231]
	s_waitcnt lgkmcnt(6)
	v_mfma_f32_16x16x32_bf16 v[132:135], v[104:107], v[12:15], v[132:135]
	s_waitcnt lgkmcnt(5)
	v_mfma_f32_16x16x32_bf16 v[136:139], v[108:111], v[4:7], v[228:231]
	s_waitcnt lgkmcnt(4)
	v_mfma_f32_16x16x32_bf16 v[136:139], v[112:115], v[12:15], v[136:139]
	s_waitcnt lgkmcnt(3)
	v_mfma_f32_16x16x32_bf16 v[140:143], v[116:119], v[4:7], v[228:231]
	s_waitcnt lgkmcnt(2)
	v_mfma_f32_16x16x32_bf16 v[140:143], v[120:123], v[12:15], v[140:143]
	s_waitcnt lgkmcnt(1)
	v_mfma_f32_16x16x32_bf16 v[144:147], v[124:127], v[4:7], v[228:231]
	s_waitcnt lgkmcnt(0)
	v_mfma_f32_16x16x32_bf16 v[144:147], v[128:131], v[12:15], v[144:147]
	v_mfma_f32_16x16x32_bf16 v[212:215], v[100:103], v[8:11], v[236:239]
	v_mfma_f32_16x16x32_bf16 v[212:215], v[104:107], v[16:19], v[212:215]
	v_max3_f32 v153, v132, v133, v134
	v_max3_f32 v154, v135, v136, v137
	v_mfma_f32_16x16x32_bf16 v[216:219], v[108:111], v[8:11], v[236:239]
	v_max3_f32 v155, v138, v139, v140
	v_max3_f32 v156, v141, v142, v143
	v_mfma_f32_16x16x32_bf16 v[216:219], v[112:115], v[16:19], v[216:219]
	s_nop 0
	v_max3_f32 v153, v153, v154, v144
	v_max3_f32 v155, v155, v156, v145
	v_max3_f32 v153, v153, v155, v146
	v_max_f32_e32 v153, v153, v147
	v_cmp_lt_f32_e32 vcc, 0x41000000, v153
	s_cbranch_vccnz .Lgqa_rare0_ga
.Lgqa_join0_ga:
	v_add_u32_e32 v208, s18, v169
	ds_read_b64 v[100:101], v208 offset:0
	ds_read_b64 v[102:103], v208 offset:32
	ds_read_b64 v[104:105], v208 offset:2304
	ds_read_b64 v[106:107], v208 offset:2336
	ds_read_b64 v[108:109], v208 offset:4608
	ds_read_b64 v[110:111], v208 offset:4640
	ds_read_b64 v[112:113], v208 offset:6912
	ds_read_b64 v[114:115], v208 offset:6944
	v_mfma_f32_16x16x32_bf16 v[220:223], v[116:119], v[8:11], v[236:239]
	v_exp_f32_e32 v132, v132
	v_exp_f32_e32 v133, v133
	v_exp_f32_e32 v134, v134
	v_exp_f32_e32 v135, v135
	v_add_f32_e32 v154, v132, v133
	v_exp_f32_e32 v136, v136
	v_add_f32_e32 v155, v134, v135
	v_exp_f32_e32 v137, v137
	v_exp_f32_e32 v138, v138
	v_add_f32_e32 v154, v154, v136
	v_mfma_f32_16x16x32_bf16 v[220:223], v[120:123], v[16:19], v[220:223]
	v_exp_f32_e32 v139, v139
	v_add_f32_e32 v155, v155, v137
	v_exp_f32_e32 v140, v140
	v_add_f32_e32 v154, v154, v138
	v_exp_f32_e32 v141, v141
	v_add_f32_e32 v155, v155, v139
	v_exp_f32_e32 v142, v142
	v_add_f32_e32 v154, v154, v140
	v_exp_f32_e32 v143, v143
	v_add_f32_e32 v155, v155, v141
	v_mfma_f32_16x16x32_bf16 v[224:227], v[124:127], v[8:11], v[236:239]
	v_exp_f32_e32 v144, v144
	v_add_f32_e32 v154, v154, v142
	v_exp_f32_e32 v145, v145
	v_add_f32_e32 v155, v155, v143
	v_exp_f32_e32 v146, v146
	v_add_f32_e32 v154, v154, v144
	v_exp_f32_e32 v147, v147
	v_add_f32_e32 v155, v155, v145
	v_add_f32_e32 v154, v154, v146
	v_add_f32_e32 v155, v155, v147
	v_mfma_f32_16x16x32_bf16 v[224:227], v[128:131], v[16:19], v[224:227]
	v_add_f32_e32 v154, v154, v155
	v_add_f32_e32 v176, v176, v154
	v_cvt_pk_bf16_f32 v228, v132, v133
	v_cvt_pk_bf16_f32 v229, v134, v135
	v_cvt_pk_bf16_f32 v230, v136, v137
	v_cvt_pk_bf16_f32 v231, v138, v139
	v_cvt_pk_bf16_f32 v232, v140, v141
	v_cvt_pk_bf16_f32 v233, v142, v143
	v_cvt_pk_bf16_f32 v234, v144, v145
	v_cvt_pk_bf16_f32 v235, v146, v147
	ds_read_b64 v[116:117], v208 offset:64
	ds_read_b64 v[118:119], v208 offset:96
	ds_read_b64 v[120:121], v208 offset:2368
	ds_read_b64 v[122:123], v208 offset:2400
	ds_read_b64 v[124:125], v208 offset:4672
	ds_read_b64 v[126:127], v208 offset:4704
	ds_read_b64 v[128:129], v208 offset:6976
	ds_read_b64 v[130:131], v208 offset:7008
	v_max3_f32 v153, v212, v213, v214
	v_max3_f32 v154, v215, v216, v217
	v_max3_f32 v155, v218, v219, v220
	v_max3_f32 v156, v221, v222, v223
	s_waitcnt lgkmcnt(14)
	v_mfma_f32_16x16x32_bf16 v[52:55], v[100:103], v[228:231], v[52:55]
	v_max3_f32 v153, v153, v154, v224
	v_max3_f32 v155, v155, v156, v225
	s_waitcnt lgkmcnt(12)
	v_mfma_f32_16x16x32_bf16 v[56:59], v[104:107], v[228:231], v[56:59]
	v_max3_f32 v153, v153, v155, v226
	v_max_f32_e32 v153, v153, v227
	v_cmp_lt_f32_e32 vcc, 0x41000000, v153
	s_cbranch_vccnz .Lgqa_rare1_ga
; DEVI float ex2(float x) { return __builtin_amdgcn_exp2f(x); }
; template <int DK>
; DEVI void attn_tile(const char* kb, const char* vb, const bool first, const bf16x8 (&qf)[2][DK / 32], f32x4 (&o)[2][4],
;                     float (&mrun)[2], float (&lsum)[2], const int l15, const int quad) {
;     ...
;   for (int qt = 0; qt < 2; ++qt)
; #pragma unroll
;     for (int ks = 0; ks < 4; ++ks) { const float nm = -mrun[qt]; s[qt][ks] = f32x4{nm, nm, nm, nm}; }
; #pragma unroll
;   for (int ks = 0; ks < 4; ++ks)
; #pragma unroll
;     for (int kk = 0; kk < NKK; ++kk) {
;       bf16x8 kf = *reinterpret_cast<const bf16x8*>(kb + (ks * 16 + l15) * KSTR + (kk * 32 + quad * 8) * 2);
;       s[0][ks] = mfma16(kf, qf[0][kk], s[0][ks]);
;       s[1][ks] = mfma16(kf, qf[1][kk], s[1][ks]);
;     }
;   bf16x8 pf[2][2];
; #pragma unroll
;   for (int qt = 0; qt < 2; ++qt) {
;     float mx = fmaxf(fmaxf(s[qt][0][0], s[qt][0][1]), fmaxf(s[qt][0][2], s[qt][0][3]));
; #pragma unroll
;     for (int ks = 1; ks < 4; ++ks) mx = fmaxf(mx, fmaxf(fmaxf(s[qt][ks][0], s[qt][ks][1]), fmaxf(s[qt][ks][2], s[qt][ks][3])));
;     if (__any(first || (mx > 8.f))) {
;       float rm = fmaxf(mx, __shfl_xor(mx, 16));
;       rm = fmaxf(rm, __shfl_xor(rm, 32));
;       const float delta = first ? rm : fmaxf(rm, 0.f);
;       const float alpha = first ? 1.f : ex2(-delta);
;       mrun[qt] += delta;
;       lsum[qt] *= alpha;
; #pragma unroll
;       for (int ks = 0; ks < 4; ++ks)
; #pragma unroll
;         for (int j = 0; j < 4; ++j) s[qt][ks][j] -= delta;
; #pragma unroll
;       for (int dd = 0; dd < 4; ++dd)
; #pragma unroll
;         for (int j = 0; j < 4; ++j) o[qt][dd][j] *= alpha;
;     }
;     float ps = 0.f;
; #pragma unroll
;     for (int ks = 0; ks < 4; ++ks)
; #pragma unroll
;       for (int j = 0; j < 4; ++j) { float pv = ex2(s[qt][ks][j]); s[qt][ks][j] = pv; ps += pv; }
;     lsum[qt] += ps;
; #pragma unroll
;     for (int k2 = 0; k2 < 2; ++k2) {
;       u32x4 wv;
;       wv[0] = pack2(s[qt][2 * k2][0], s[qt][2 * k2][1]);
;       wv[1] = pack2(s[qt][2 * k2][2], s[qt][2 * k2][3]);
;       wv[2] = pack2(s[qt][2 * k2 + 1][0], s[qt][2 * k2 + 1][1]);
;       wv[3] = pack2(s[qt][2 * k2 + 1][2], s[qt][2 * k2 + 1][3]);
;       pf[qt][k2] = as_bf8(wv);
;     }
;   }
; #pragma unroll
;   for (int dd = 0; dd < 4; ++dd)
; #pragma unroll
;     for (int k2 = 0; k2 < 2; ++k2) {
.Lgqa_join1_ga:
	s_waitcnt lgkmcnt(10)
	v_mfma_f32_16x16x32_bf16 v[60:63], v[108:111], v[228:231], v[60:63]
	v_exp_f32_e32 v212, v212
	v_exp_f32_e32 v213, v213
	v_exp_f32_e32 v214, v214
	v_exp_f32_e32 v215, v215
	v_add_f32_e32 v154, v212, v213
	v_exp_f32_e32 v216, v216
	s_waitcnt lgkmcnt(8)
	v_mfma_f32_16x16x32_bf16 v[64:67], v[112:115], v[228:231], v[64:67]
	v_add_f32_e32 v155, v214, v215
	v_exp_f32_e32 v217, v217
	v_exp_f32_e32 v218, v218
	v_add_f32_e32 v154, v154, v216
	v_exp_f32_e32 v219, v219
	v_add_f32_e32 v155, v155, v217
	v_exp_f32_e32 v220, v220
	s_waitcnt lgkmcnt(6)
	v_mfma_f32_16x16x32_bf16 v[52:55], v[116:119], v[232:235], v[52:55]
	v_add_f32_e32 v154, v154, v218
	v_exp_f32_e32 v221, v221
	v_add_f32_e32 v155, v155, v219
	v_exp_f32_e32 v222, v222
	v_add_f32_e32 v154, v154, v220
	v_exp_f32_e32 v223, v223
	v_add_f32_e32 v155, v155, v221
	s_waitcnt lgkmcnt(4)
	v_mfma_f32_16x16x32_bf16 v[56:59], v[120:123], v[232:235], v[56:59]
	v_exp_f32_e32 v224, v224
	v_add_f32_e32 v154, v154, v222
	v_exp_f32_e32 v225, v225
	v_add_f32_e32 v155, v155, v223
	v_exp_f32_e32 v226, v226
	v_add_f32_e32 v154, v154, v224
	s_waitcnt lgkmcnt(2)
	v_mfma_f32_16x16x32_bf16 v[60:63], v[124:127], v[232:235], v[60:63]
	v_exp_f32_e32 v227, v227
	v_add_f32_e32 v155, v155, v225
	v_add_f32_e32 v154, v154, v226
	v_add_f32_e32 v155, v155, v227
	v_add_f32_e32 v154, v154, v155
	v_add_f32_e32 v175, v175, v154
	v_cvt_pk_bf16_f32 v236, v212, v213
	s_waitcnt lgkmcnt(0)
	v_mfma_f32_16x16x32_bf16 v[64:67], v[128:131], v[232:235], v[64:67]
	v_cvt_pk_bf16_f32 v237, v214, v215
	v_cvt_pk_bf16_f32 v238, v216, v217
	v_cvt_pk_bf16_f32 v239, v218, v219
	v_cvt_pk_bf16_f32 v240, v220, v221
	v_cvt_pk_bf16_f32 v241, v222, v223
	v_cvt_pk_bf16_f32 v242, v224, v225
	v_cvt_pk_bf16_f32 v243, v226, v227
	s_nop 0
	v_mfma_f32_16x16x32_bf16 v[36:39], v[100:103], v[236:239], v[36:39]
	v_mfma_f32_16x16x32_bf16 v[40:43], v[104:107], v[236:239], v[40:43]
	v_mfma_f32_16x16x32_bf16 v[44:47], v[108:111], v[236:239], v[44:47]
	v_mfma_f32_16x16x32_bf16 v[48:51], v[112:115], v[236:239], v[48:51]
	v_xor_b32_e32 v228, 0x80000000, v172
	v_mov_b32_e32 v229, v228
	v_mfma_f32_16x16x32_bf16 v[36:39], v[116:119], v[240:243], v[36:39]
	v_mfma_f32_16x16x32_bf16 v[40:43], v[120:123], v[240:243], v[40:43]
	v_mfma_f32_16x16x32_bf16 v[44:47], v[124:127], v[240:243], v[44:47]
	v_mfma_f32_16x16x32_bf16 v[48:51], v[128:131], v[240:243], v[48:51]
	v_mov_b32_e32 v230, v228
	v_mov_b32_e32 v231, v228
	v_xor_b32_e32 v236, 0x80000000, v173
	v_mov_b32_e32 v237, v236
	v_mov_b32_e32 v238, v236
	v_mov_b32_e32 v239, v236
	v_add_u32_e32 v211, s18, v168
	ds_read_b128 v[100:103], v211
	ds_read_b128 v[104:107], v211 offset:64
	ds_read_b128 v[108:111], v211 offset:2560
	ds_read_b128 v[112:115], v211 offset:2624
	ds_read_b128 v[116:119], v211 offset:5120
	ds_read_b128 v[120:123], v211 offset:5184
	ds_read_b128 v[124:127], v211 offset:7680
	ds_read_b128 v[128:131], v211 offset:7744
	s_waitcnt lgkmcnt(7)
	v_mfma_f32_16x16x32_bf16 v[132:135], v[100:103], v[20:23], v[228:231]
	s_waitcnt lgkmcnt(6)
	v_mfma_f32_16x16x32_bf16 v[132:135], v[104:107], v[24:27], v[132:135]
	s_waitcnt lgkmcnt(5)
	v_mfma_f32_16x16x32_bf16 v[136:139], v[108:111], v[20:23], v[228:231]
	s_waitcnt lgkmcnt(4)
	v_mfma_f32_16x16x32_bf16 v[136:139], v[112:115], v[24:27], v[136:139]
	s_waitcnt lgkmcnt(3)
	v_mfma_f32_16x16x32_bf16 v[140:143], v[116:119], v[20:23], v[228:231]
	s_waitcnt lgkmcnt(2)
	v_mfma_f32_16x16x32_bf16 v[140:143], v[120:123], v[24:27], v[140:143]
	s_waitcnt lgkmcnt(1)
	v_mfma_f32_16x16x32_bf16 v[144:147], v[124:127], v[20:23], v[228:231]
	s_waitcnt lgkmcnt(0)
	v_mfma_f32_16x16x32_bf16 v[144:147], v[128:131], v[24:27], v[144:147]
	v_mfma_f32_16x16x32_bf16 v[212:215], v[100:103], v[28:31], v[236:239]
	v_mfma_f32_16x16x32_bf16 v[212:215], v[104:107], v[32:35], v[212:215]
	v_max3_f32 v153, v132, v133, v134
	v_max3_f32 v154, v135, v136, v137
	v_mfma_f32_16x16x32_bf16 v[216:219], v[108:111], v[28:31], v[236:239]
	v_max3_f32 v155, v138, v139, v140
	v_max3_f32 v156, v141, v142, v143
	v_mfma_f32_16x16x32_bf16 v[216:219], v[112:115], v[32:35], v[216:219]
	s_nop 0
	v_max3_f32 v153, v153, v154, v144
	v_max3_f32 v155, v155, v156, v145
	v_max3_f32 v153, v153, v155, v146
	v_max_f32_e32 v153, v153, v147
	v_cmp_lt_f32_e32 vcc, 0x41000000, v153
	s_cbranch_vccnz .Lgqa_rare0_gb
; DEVI unsigned pack2(float a, float b) { f32x2_t v = {a, b}; bf16x2_t r = __builtin_convertvector(v, bf16x2_t); return *reinterpret_cast<unsigned*>(&r); }
; DEVI float ex2(float x) { return __builtin_amdgcn_exp2f(x); }
; DEVI f32x4 mfma16(bf16x8 a, bf16x8 b, f32x4 c) { return __builtin_amdgcn_mfma_f32_16x16x32_bf16(a, b, c, 0, 0, 0); }
; template <int DK>
; DEVI void attn_tile(const char* kb, const char* vb, const bool first, const bf16x8 (&qf)[2][DK / 32], f32x4 (&o)[2][4],
;                     float (&mrun)[2], float (&lsum)[2], const int l15, const int quad) {
;     ...
;     float ps = 0.f;
; #pragma unroll
;     for (int ks = 0; ks < 4; ++ks)
; #pragma unroll
;       for (int j = 0; j < 4; ++j) { float pv = ex2(s[qt][ks][j]); s[qt][ks][j] = pv; ps += pv; }
;     lsum[qt] += ps;
; #pragma unroll
;     for (int k2 = 0; k2 < 2; ++k2) {
;       u32x4 wv;
;       wv[0] = pack2(s[qt][2 * k2][0], s[qt][2 * k2][1]);
;       wv[1] = pack2(s[qt][2 * k2][2], s[qt][2 * k2][3]);
;       wv[2] = pack2(s[qt][2 * k2 + 1][0], s[qt][2 * k2 + 1][1]);
;       wv[3] = pack2(s[qt][2 * k2 + 1][2], s[qt][2 * k2 + 1][3]);
;       pf[qt][k2] = as_bf8(wv);
;     }
;   }
; #pragma unroll
;   for (int dd = 0; dd < 4; ++dd)
; #pragma unroll
;     for (int k2 = 0; k2 < 2; ++k2) {
;       u32x2 lo = *reinterpret_cast<const u32x2*>(vb + (dd * 16 + l15) * 144 + (k2 * 32 + quad * 4) * 2);
;       u32x2 hi = *reinterpret_cast<const u32x2*>(vb + (dd * 16 + l15) * 144 + (k2 * 32 + 16 + quad * 4) * 2);
;       u32x4 vv = {lo[0], lo[1], hi[0], hi[1]};
;       bf16x8 vf = as_bf8(vv);
;       o[0][dd] = mfma16(vf, pf[0][k2], o[0][dd]);
;       o[1][dd] = mfma16(vf, pf[1][k2], o[1][dd]);
;     }
; template <int DK, int QP>
; DEVI void attn_item(const bf* __restrict__ Q, const bf* __restrict__ Kp, const bf* __restrict__ Vt, bf* __restrict__ outp  ,
;                     long row_base, int j0, int nkeys, char* smem) {
;     ...
;     AWRITE(rkA, rvA, (t + 1) & 1);
;     __syncthreads();
.Lgqa_join0_gb:
	v_add_u32_e32 v208, s18, v169
	ds_read_b64 v[100:101], v208 offset:0
	ds_read_b64 v[102:103], v208 offset:32
	ds_read_b64 v[104:105], v208 offset:2304
	ds_read_b64 v[106:107], v208 offset:2336
	ds_read_b64 v[108:109], v208 offset:4608
	ds_read_b64 v[110:111], v208 offset:4640
	ds_read_b64 v[112:113], v208 offset:6912
	ds_read_b64 v[114:115], v208 offset:6944
	v_mfma_f32_16x16x32_bf16 v[220:223], v[116:119], v[28:31], v[236:239]
	v_exp_f32_e32 v132, v132
	v_exp_f32_e32 v133, v133
	v_exp_f32_e32 v134, v134
	v_exp_f32_e32 v135, v135
	v_add_f32_e32 v154, v132, v133
	v_exp_f32_e32 v136, v136
	v_add_f32_e32 v155, v134, v135
	v_exp_f32_e32 v137, v137
	v_exp_f32_e32 v138, v138
	v_add_f32_e32 v154, v154, v136
	v_mfma_f32_16x16x32_bf16 v[220:223], v[120:123], v[32:35], v[220:223]
	v_exp_f32_e32 v139, v139
	v_add_f32_e32 v155, v155, v137
	v_exp_f32_e32 v140, v140
	v_add_f32_e32 v154, v154, v138
	v_exp_f32_e32 v141, v141
	v_add_f32_e32 v155, v155, v139
	v_exp_f32_e32 v142, v142
	v_add_f32_e32 v154, v154, v140
	v_exp_f32_e32 v143, v143
	v_add_f32_e32 v155, v155, v141
	v_mfma_f32_16x16x32_bf16 v[224:227], v[124:127], v[28:31], v[236:239]
	v_exp_f32_e32 v144, v144
	v_add_f32_e32 v154, v154, v142
	v_exp_f32_e32 v145, v145
	v_add_f32_e32 v155, v155, v143
	v_exp_f32_e32 v146, v146
	v_add_f32_e32 v154, v154, v144
	v_exp_f32_e32 v147, v147
	v_add_f32_e32 v155, v155, v145
	v_add_f32_e32 v154, v154, v146
	v_add_f32_e32 v155, v155, v147
	v_mfma_f32_16x16x32_bf16 v[224:227], v[128:131], v[32:35], v[224:227]
	v_add_f32_e32 v154, v154, v155
	v_add_f32_e32 v174, v174, v154
	v_cvt_pk_bf16_f32 v228, v132, v133
	v_cvt_pk_bf16_f32 v229, v134, v135
	v_cvt_pk_bf16_f32 v230, v136, v137
	v_cvt_pk_bf16_f32 v231, v138, v139
	v_cvt_pk_bf16_f32 v232, v140, v141
	v_cvt_pk_bf16_f32 v233, v142, v143
	v_cvt_pk_bf16_f32 v234, v144, v145
	v_cvt_pk_bf16_f32 v235, v146, v147
	ds_read_b64 v[116:117], v208 offset:64
	ds_read_b64 v[118:119], v208 offset:96
	ds_read_b64 v[120:121], v208 offset:2368
	ds_read_b64 v[122:123], v208 offset:2400
	ds_read_b64 v[124:125], v208 offset:4672
	ds_read_b64 v[126:127], v208 offset:4704
	ds_read_b64 v[128:129], v208 offset:6976
	ds_read_b64 v[130:131], v208 offset:7008
	v_max3_f32 v153, v212, v213, v214
	v_max3_f32 v154, v215, v216, v217
	v_max3_f32 v155, v218, v219, v220
	v_max3_f32 v156, v221, v222, v223
	s_waitcnt lgkmcnt(14)
	v_mfma_f32_16x16x32_bf16 v[72:75], v[100:103], v[228:231], v[72:75]
	v_max3_f32 v153, v153, v154, v224
	v_max3_f32 v155, v155, v156, v225
	s_waitcnt lgkmcnt(12)
	v_mfma_f32_16x16x32_bf16 v[80:83], v[104:107], v[228:231], v[80:83]
	v_max3_f32 v153, v153, v155, v226
	v_max_f32_e32 v153, v153, v227
	v_cmp_lt_f32_e32 vcc, 0x41000000, v153
	s_cbranch_vccnz .Lgqa_rare1_gb
.Lgqa_join1_gb:
	s_waitcnt lgkmcnt(10)
	v_mfma_f32_16x16x32_bf16 v[88:91], v[108:111], v[228:231], v[88:91]
	v_exp_f32_e32 v212, v212
	v_exp_f32_e32 v213, v213
	v_exp_f32_e32 v214, v214
	v_exp_f32_e32 v215, v215
	v_add_f32_e32 v154, v212, v213
	v_exp_f32_e32 v216, v216
	s_waitcnt lgkmcnt(8)
	v_mfma_f32_16x16x32_bf16 v[96:99], v[112:115], v[228:231], v[96:99]
	v_add_f32_e32 v155, v214, v215
	v_exp_f32_e32 v217, v217
	v_exp_f32_e32 v218, v218
	v_add_f32_e32 v154, v154, v216
	v_exp_f32_e32 v219, v219
	v_add_f32_e32 v155, v155, v217
	v_exp_f32_e32 v220, v220
	s_waitcnt lgkmcnt(6)
	v_mfma_f32_16x16x32_bf16 v[72:75], v[116:119], v[232:235], v[72:75]
	v_add_f32_e32 v154, v154, v218
	v_exp_f32_e32 v221, v221
	v_add_f32_e32 v155, v155, v219
	v_exp_f32_e32 v222, v222
	v_add_f32_e32 v154, v154, v220
	v_exp_f32_e32 v223, v223
	v_add_f32_e32 v155, v155, v221
	s_waitcnt lgkmcnt(4)
	v_mfma_f32_16x16x32_bf16 v[80:83], v[120:123], v[232:235], v[80:83]
	v_exp_f32_e32 v224, v224
	v_add_f32_e32 v154, v154, v222
	v_exp_f32_e32 v225, v225
	v_add_f32_e32 v155, v155, v223
	v_exp_f32_e32 v226, v226
	v_add_f32_e32 v154, v154, v224
	s_waitcnt lgkmcnt(2)
	v_mfma_f32_16x16x32_bf16 v[88:91], v[124:127], v[232:235], v[88:91]
	v_exp_f32_e32 v227, v227
	v_add_f32_e32 v155, v155, v225
	v_add_f32_e32 v154, v154, v226
	v_add_f32_e32 v155, v155, v227
	v_add_f32_e32 v154, v154, v155
	v_add_f32_e32 v210, v210, v154
	v_cvt_pk_bf16_f32 v236, v212, v213
	s_waitcnt lgkmcnt(0)
	v_mfma_f32_16x16x32_bf16 v[96:99], v[128:131], v[232:235], v[96:99]
	v_cvt_pk_bf16_f32 v237, v214, v215
	v_cvt_pk_bf16_f32 v238, v216, v217
	v_cvt_pk_bf16_f32 v239, v218, v219
	v_cvt_pk_bf16_f32 v240, v220, v221
	v_cvt_pk_bf16_f32 v241, v222, v223
	v_cvt_pk_bf16_f32 v242, v224, v225
	v_cvt_pk_bf16_f32 v243, v226, v227
	s_nop 0
	v_mfma_f32_16x16x32_bf16 v[68:71], v[100:103], v[236:239], v[68:71]
	v_mfma_f32_16x16x32_bf16 v[76:79], v[104:107], v[236:239], v[76:79]
	s_xor_b32 s18, s18, 0x4c00
	v_xor_b32_e32 v228, 0x80000000, v159
	v_mov_b32_e32 v229, v228
	v_mfma_f32_16x16x32_bf16 v[84:87], v[108:111], v[236:239], v[84:87]
	v_mov_b32_e32 v230, v228
	v_mov_b32_e32 v231, v228
	v_mfma_f32_16x16x32_bf16 v[92:95], v[112:115], v[236:239], v[92:95]
	v_add_u32_e32 v209, s18, v170
	s_waitcnt vmcnt(3)
	ds_write_b128 v209, v[192:195]
	v_mfma_f32_16x16x32_bf16 v[68:71], v[116:119], v[240:243], v[68:71]
	v_mfma_f32_16x16x32_bf16 v[76:79], v[120:123], v[240:243], v[76:79]
	v_add_u32_e32 v208, s18, v171
	s_waitcnt vmcnt(2)
	ds_write_b128 v208, v[196:199]
	v_mfma_f32_16x16x32_bf16 v[84:87], v[124:127], v[240:243], v[84:87]
	v_add_u32_e32 v209, s18, v177
	s_waitcnt vmcnt(1)
	ds_write_b128 v209, v[244:247] offset:10240
	v_mfma_f32_16x16x32_bf16 v[92:95], v[128:131], v[240:243], v[92:95]
	s_waitcnt vmcnt(0)
	ds_write_b128 v209, v[164:167] offset:14848
	v_xor_b32_e32 v236, 0x80000000, v157
	v_mov_b32_e32 v237, v236
	v_mov_b32_e32 v238, v236
	v_mov_b32_e32 v239, v236
	s_add_i32 s11, s11, 1
	s_cmp_lg_u32 s11, s3
	s_waitcnt lgkmcnt(0)
	s_barrier
	s_cbranch_scc1 .Lgqa_loop_g
	s_branch .Lgqa_exit_g
; DEVI float ex2(float x) { return __builtin_amdgcn_exp2f(x); }
; template <int DK>
; DEVI void attn_tile(const char* kb, const char* vb, const bool first, const bf16x8 (&qf)[2][DK / 32], f32x4 (&o)[2][4],
;                     float (&mrun)[2], float (&lsum)[2], const int l15, const int quad) {
;     ...
;     if (__any(first || (mx > 8.f))) {
;       float rm = fmaxf(mx, __shfl_xor(mx, 16));
;       rm = fmaxf(rm, __shfl_xor(rm, 32));
;       const float delta = first ? rm : fmaxf(rm, 0.f);
;       const float alpha = first ? 1.f : ex2(-delta);
;       mrun[qt] += delta;
;       lsum[qt] *= alpha;
; #pragma unroll
;       for (int ks = 0; ks < 4; ++ks)
; #pragma unroll
;         for (int j = 0; j < 4; ++j) s[qt][ks][j] -= delta;
; #pragma unroll
;       for (int dd = 0; dd < 4; ++dd)
; #pragma unroll
;         for (int j = 0; j < 4; ++j) o[qt][dd][j] *= alpha;
;     }
.Lgqa_rare0_ga:
	v_cmp_lt_i32_e32 vcc, v186, v184
	s_nop 1
	v_cndmask_b32_e32 v154, v183, v186, vcc
	v_lshlrev_b32_e32 v154, 2, v154
	ds_bpermute_b32 v154, v154, v153
	v_cmp_lt_i32_e32 vcc, v185, v184
	s_waitcnt lgkmcnt(0)
	v_max_f32_e32 v153, v153, v154
	v_cndmask_b32_e32 v154, v183, v185, vcc
	v_lshlrev_b32_e32 v154, 2, v154
	ds_bpermute_b32 v154, v154, v153
	s_waitcnt lgkmcnt(0)
	v_max3_f32 v153, v153, v154, 0
	v_exp_f32_e64 v155, -v153
	v_add_f32_e32 v159, v159, v153
	v_sub_f32_e32 v132, v132, v153
	v_sub_f32_e32 v133, v133, v153
	v_sub_f32_e32 v134, v134, v153
	v_sub_f32_e32 v135, v135, v153
	v_sub_f32_e32 v136, v136, v153
	v_sub_f32_e32 v137, v137, v153
	v_sub_f32_e32 v138, v138, v153
	v_sub_f32_e32 v139, v139, v153
	v_sub_f32_e32 v140, v140, v153
	v_sub_f32_e32 v141, v141, v153
	v_sub_f32_e32 v142, v142, v153
	v_sub_f32_e32 v143, v143, v153
	v_sub_f32_e32 v144, v144, v153
	v_sub_f32_e32 v145, v145, v153
	v_sub_f32_e32 v146, v146, v153
	v_sub_f32_e32 v147, v147, v153
	v_mul_f32_e32 v176, v176, v155
	v_mul_f32_e32 v52, v52, v155
	v_mul_f32_e32 v53, v53, v155
	v_mul_f32_e32 v54, v54, v155
	v_mul_f32_e32 v55, v55, v155
	v_mul_f32_e32 v56, v56, v155
	v_mul_f32_e32 v57, v57, v155
	v_mul_f32_e32 v58, v58, v155
	v_mul_f32_e32 v59, v59, v155
	v_mul_f32_e32 v60, v60, v155
	v_mul_f32_e32 v61, v61, v155
	v_mul_f32_e32 v62, v62, v155
	v_mul_f32_e32 v63, v63, v155
	v_mul_f32_e32 v64, v64, v155
	v_mul_f32_e32 v65, v65, v155
	v_mul_f32_e32 v66, v66, v155
	v_mul_f32_e32 v67, v67, v155
	s_branch .Lgqa_join0_ga
.Lgqa_rare1_ga:
	v_cmp_lt_i32_e32 vcc, v186, v184
	s_nop 1
	v_cndmask_b32_e32 v154, v183, v186, vcc
	v_lshlrev_b32_e32 v154, 2, v154
	ds_bpermute_b32 v154, v154, v153
	v_cmp_lt_i32_e32 vcc, v185, v184
	s_waitcnt lgkmcnt(0)
	v_max_f32_e32 v153, v153, v154
	v_cndmask_b32_e32 v154, v183, v185, vcc
	v_lshlrev_b32_e32 v154, 2, v154
	ds_bpermute_b32 v154, v154, v153
	s_waitcnt lgkmcnt(0)
	v_max3_f32 v153, v153, v154, 0
	v_exp_f32_e64 v155, -v153
	v_add_f32_e32 v157, v157, v153
	v_sub_f32_e32 v212, v212, v153
	v_sub_f32_e32 v213, v213, v153
	v_sub_f32_e32 v214, v214, v153
	v_sub_f32_e32 v215, v215, v153
	v_sub_f32_e32 v216, v216, v153
	v_sub_f32_e32 v217, v217, v153
	v_sub_f32_e32 v218, v218, v153
	v_sub_f32_e32 v219, v219, v153
	v_sub_f32_e32 v220, v220, v153
	v_sub_f32_e32 v221, v221, v153
	v_sub_f32_e32 v222, v222, v153
	v_sub_f32_e32 v223, v223, v153
	v_sub_f32_e32 v224, v224, v153
	v_sub_f32_e32 v225, v225, v153
	v_sub_f32_e32 v226, v226, v153
	v_sub_f32_e32 v227, v227, v153
	v_mul_f32_e32 v175, v175, v155
	v_mul_f32_e32 v36, v36, v155
	v_mul_f32_e32 v37, v37, v155
	v_mul_f32_e32 v38, v38, v155
	v_mul_f32_e32 v39, v39, v155
	v_mul_f32_e32 v40, v40, v155
	v_mul_f32_e32 v41, v41, v155
	v_mul_f32_e32 v42, v42, v155
	v_mul_f32_e32 v43, v43, v155
	v_mul_f32_e32 v44, v44, v155
	v_mul_f32_e32 v45, v45, v155
	v_mul_f32_e32 v46, v46, v155
	v_mul_f32_e32 v47, v47, v155
	v_mul_f32_e32 v48, v48, v155
	v_mul_f32_e32 v49, v49, v155
	v_mul_f32_e32 v50, v50, v155
	v_mul_f32_e32 v51, v51, v155
	s_branch .Lgqa_join1_ga
.Lgqa_rare0_gb:
	v_cmp_lt_i32_e32 vcc, v186, v184
	s_nop 1
	v_cndmask_b32_e32 v154, v183, v186, vcc
	v_lshlrev_b32_e32 v154, 2, v154
	ds_bpermute_b32 v154, v154, v153
	v_cmp_lt_i32_e32 vcc, v185, v184
	s_waitcnt lgkmcnt(0)
	v_max_f32_e32 v153, v153, v154
	v_cndmask_b32_e32 v154, v183, v185, vcc
	v_lshlrev_b32_e32 v154, 2, v154
	ds_bpermute_b32 v154, v154, v153
	s_waitcnt lgkmcnt(0)
	v_max3_f32 v153, v153, v154, 0
	v_exp_f32_e64 v155, -v153
	v_add_f32_e32 v172, v172, v153
	v_sub_f32_e32 v132, v132, v153
	v_sub_f32_e32 v133, v133, v153
	v_sub_f32_e32 v134, v134, v153
	v_sub_f32_e32 v135, v135, v153
	v_sub_f32_e32 v136, v136, v153
	v_sub_f32_e32 v137, v137, v153
	v_sub_f32_e32 v138, v138, v153
	v_sub_f32_e32 v139, v139, v153
	v_sub_f32_e32 v140, v140, v153
	v_sub_f32_e32 v141, v141, v153
	v_sub_f32_e32 v142, v142, v153
	v_sub_f32_e32 v143, v143, v153
	v_sub_f32_e32 v144, v144, v153
	v_sub_f32_e32 v145, v145, v153
	v_sub_f32_e32 v146, v146, v153
	v_sub_f32_e32 v147, v147, v153
	v_mul_f32_e32 v174, v174, v155
	v_mul_f32_e32 v72, v72, v155
	v_mul_f32_e32 v73, v73, v155
	v_mul_f32_e32 v74, v74, v155
	v_mul_f32_e32 v75, v75, v155
	v_mul_f32_e32 v80, v80, v155
	v_mul_f32_e32 v81, v81, v155
	v_mul_f32_e32 v82, v82, v155
	v_mul_f32_e32 v83, v83, v155
	v_mul_f32_e32 v88, v88, v155
	v_mul_f32_e32 v89, v89, v155
	v_mul_f32_e32 v90, v90, v155
	v_mul_f32_e32 v91, v91, v155
	v_mul_f32_e32 v96, v96, v155
	v_mul_f32_e32 v97, v97, v155
	v_mul_f32_e32 v98, v98, v155
	v_mul_f32_e32 v99, v99, v155
	s_branch .Lgqa_join0_gb
.Lgqa_rare1_gb:
	v_cmp_lt_i32_e32 vcc, v186, v184
	s_nop 1
	v_cndmask_b32_e32 v154, v183, v186, vcc
	v_lshlrev_b32_e32 v154, 2, v154
	ds_bpermute_b32 v154, v154, v153
	v_cmp_lt_i32_e32 vcc, v185, v184
	s_waitcnt lgkmcnt(0)
	v_max_f32_e32 v153, v153, v154
	v_cndmask_b32_e32 v154, v183, v185, vcc
	v_lshlrev_b32_e32 v154, 2, v154
	ds_bpermute_b32 v154, v154, v153
	s_waitcnt lgkmcnt(0)
	v_max3_f32 v153, v153, v154, 0
	v_exp_f32_e64 v155, -v153
	v_add_f32_e32 v173, v173, v153
	v_sub_f32_e32 v212, v212, v153
	v_sub_f32_e32 v213, v213, v153
	v_sub_f32_e32 v214, v214, v153
	v_sub_f32_e32 v215, v215, v153
	v_sub_f32_e32 v216, v216, v153
	v_sub_f32_e32 v217, v217, v153
	v_sub_f32_e32 v218, v218, v153
	v_sub_f32_e32 v219, v219, v153
	v_sub_f32_e32 v220, v220, v153
	v_sub_f32_e32 v221, v221, v153
	v_sub_f32_e32 v222, v222, v153
	v_sub_f32_e32 v223, v223, v153
	v_sub_f32_e32 v224, v224, v153
	v_sub_f32_e32 v225, v225, v153
	v_sub_f32_e32 v226, v226, v153
	v_sub_f32_e32 v227, v227, v153
	v_mul_f32_e32 v210, v210, v155
	v_mul_f32_e32 v68, v68, v155
	v_mul_f32_e32 v69, v69, v155
	v_mul_f32_e32 v70, v70, v155
	v_mul_f32_e32 v71, v71, v155
	v_mul_f32_e32 v76, v76, v155
	v_mul_f32_e32 v77, v77, v155
	v_mul_f32_e32 v78, v78, v155
	v_mul_f32_e32 v79, v79, v155
	v_mul_f32_e32 v84, v84, v155
	v_mul_f32_e32 v85, v85, v155
	v_mul_f32_e32 v86, v86, v155
	v_mul_f32_e32 v87, v87, v155
	v_mul_f32_e32 v92, v92, v155
	v_mul_f32_e32 v93, v93, v155
	v_mul_f32_e32 v94, v94, v155
	v_mul_f32_e32 v95, v95, v155
	s_branch .Lgqa_join1_gb
; DEVI unsigned pack2(float a, float b) { f32x2_t v = {a, b}; bf16x2_t r = __builtin_convertvector(v, bf16x2_t); return *reinterpret_cast<unsigned*>(&r); }
; template <int DK, int QP>
; DEVI void attn_item(const bf* __restrict__ Q, const bf* __restrict__ Kp, const bf* __restrict__ Vt, bf* __restrict__ outp  ,
;                     long row_base, int j0, int nkeys, char* smem) {
;     ...
; #pragma unroll
;   for (int pr = 0; pr < QP; ++pr)
; #pragma unroll
;     for (int qt = 0; qt < 2; ++qt) {
;       float ls = lsum[pr][qt];
;       ls += __shfl_xor(ls, 16);
;       ls += __shfl_xor(ls, 32);
;       const float inv = 1.f / ls;
;       const long row = row_base + j0 + w * (32 * QP) + pr * 32 + qt * 16 + l15;
; #pragma unroll
;       for (int dd = 0; dd < 4; ++dd) {
;         u32x2 ov;
;         ov[0] = pack2(o[pr][qt][dd][0] * inv, o[pr][qt][dd][1] * inv);
;         ov[1] = pack2(o[pr][qt][dd][2] * inv, o[pr][qt][dd][3] * inv);
;         *reinterpret_cast<u32x2*>(outp + row * DM + dd * 16 + quad * 4) = ov;
;       }
;     }
.Lgqa_exit_g:
.LBB0_624:
	v_cmp_lt_i32_e32 vcc, v186, v184
	v_readlane_b32 s40, v251, 58
	s_lshl_b32 s3, s25, 7
	v_cndmask_b32_e32 v1, v183, v186, vcc
	v_lshlrev_b32_e32 v1, 2, v1
	ds_bpermute_b32 v2, v1, v176
	v_cmp_lt_i32_e32 vcc, v185, v184
	v_readlane_b32 s46, v252, 0
	v_readlane_b32 s47, v252, 1
	v_cndmask_b32_e32 v4, v183, v185, vcc
	v_lshlrev_b32_e32 v12, 2, v4
	s_waitcnt lgkmcnt(0)
	v_add_f32_e32 v2, v176, v2
	ds_bpermute_b32 v6, v12, v2
	s_add_u32 s10, s46, s3
	s_mul_i32 s3, s24, 0x4100
	s_addc_u32 s11, s47, 0
	s_ashr_i32 s12, s3, 31
	s_add_u32 s2, s3, s2
	s_addc_u32 s3, s12, 0
	v_ashrrev_i32_e32 v151, 31, v150
	s_waitcnt lgkmcnt(0)
	v_add_f32_e32 v2, v2, v6
	v_lshl_add_u64 v[4:5], s[2:3], 0, v[150:151]
	v_div_scale_f32 v8, s[2:3], v2, v2, 1.0
	v_rcp_f32_e32 v9, v8
	v_mov_b32_e32 v149, v3
	v_lshl_add_u64 v[4:5], v[4:5], 0, v[148:149]
	v_mov_b32_e32 v163, v3
	v_fma_f32 v10, -v8, v9, 1.0
	v_fmac_f32_e32 v9, v10, v9
	v_div_scale_f32 v10, vcc, 1.0, v2, 1.0
	v_mul_f32_e32 v11, v10, v9
	v_fma_f32 v13, -v8, v11, v10
	v_fmac_f32_e32 v11, v13, v9
	v_fma_f32 v8, -v8, v11, v10
	ds_bpermute_b32 v10, v1, v175
	v_div_fmas_f32 v8, v8, v9, v11
	v_lshl_add_u64 v[6:7], s[10:11], 0, v[162:163]
	v_div_fixup_f32 v2, v8, v2, 1.0
	v_lshlrev_b64 v[4:5], 11, v[4:5]
	s_waitcnt lgkmcnt(0)
	v_add_f32_e32 v10, v175, v10
	ds_bpermute_b32 v11, v12, v10
	v_lshl_add_u64 v[4:5], v[6:7], 0, v[4:5]
	v_pk_mul_f32 v[6:7], v[52:53], v[2:3] op_sel_hi:[1,0]
	v_pk_mul_f32 v[8:9], v[54:55], v[2:3] op_sel_hi:[1,0]
	v_cvt_pk_bf16_f32 v6, v6, v7
	s_waitcnt lgkmcnt(0)
	v_add_f32_e32 v10, v10, v11
	v_cvt_pk_bf16_f32 v7, v8, v9
	v_div_scale_f32 v11, s[2:3], v10, v10, 1.0
	global_store_dwordx2 v[4:5], v[6:7], off offset:1536
	v_pk_mul_f32 v[6:7], v[56:57], v[2:3] op_sel_hi:[1,0]
	v_pk_mul_f32 v[8:9], v[58:59], v[2:3] op_sel_hi:[1,0]
	v_rcp_f32_e32 v13, v11
	v_cvt_pk_bf16_f32 v6, v6, v7
	v_cvt_pk_bf16_f32 v7, v8, v9
	global_store_dwordx2 v[4:5], v[6:7], off offset:1568
	v_pk_mul_f32 v[6:7], v[60:61], v[2:3] op_sel_hi:[1,0]
	v_pk_mul_f32 v[8:9], v[62:63], v[2:3] op_sel_hi:[1,0]
	v_cvt_pk_bf16_f32 v6, v6, v7
	v_cvt_pk_bf16_f32 v7, v8, v9
	global_store_dwordx2 v[4:5], v[6:7], off offset:1600
	v_pk_mul_f32 v[6:7], v[64:65], v[2:3] op_sel_hi:[1,0]
	v_pk_mul_f32 v[8:9], v[66:67], v[2:3] op_sel_hi:[1,0]
	v_fma_f32 v2, -v11, v13, 1.0
	v_cvt_pk_bf16_f32 v6, v6, v7
	v_cvt_pk_bf16_f32 v7, v8, v9
	v_fmac_f32_e32 v13, v2, v13
	v_div_scale_f32 v2, vcc, 1.0, v10, 1.0
	global_store_dwordx2 v[4:5], v[6:7], off offset:1632
	v_mul_f32_e32 v6, v2, v13
	v_fma_f32 v7, -v11, v6, v2
	v_fmac_f32_e32 v6, v7, v13
	v_fma_f32 v2, -v11, v6, v2
	v_div_fmas_f32 v2, v2, v13, v6
	ds_bpermute_b32 v13, v1, v174
	v_div_fixup_f32 v2, v2, v10, 1.0
	v_pk_mul_f32 v[6:7], v[36:37], v[2:3] op_sel_hi:[1,0]
	v_pk_mul_f32 v[8:9], v[38:39], v[2:3] op_sel_hi:[1,0]
	s_mov_b32 s2, 0x8000
	s_waitcnt lgkmcnt(0)
	v_add_f32_e32 v13, v174, v13
	ds_bpermute_b32 v14, v12, v13
	v_cvt_pk_bf16_f32 v6, v6, v7
	v_cvt_pk_bf16_f32 v7, v8, v9
	v_add_co_u32_e32 v8, vcc, s2, v4
	s_waitcnt lgkmcnt(0)
; DEVI unsigned pack2(float a, float b) { f32x2_t v = {a, b}; bf16x2_t r = __builtin_convertvector(v, bf16x2_t); return *reinterpret_cast<unsigned*>(&r); }
; template <int DK, int QP>
; DEVI void attn_item(const bf* __restrict__ Q, const bf* __restrict__ Kp, const bf* __restrict__ Vt, bf* __restrict__ outp  ,
;                     long row_base, int j0, int nkeys, char* smem) {
;     ...
; #pragma unroll
;   for (int pr = 0; pr < QP; ++pr)
; #pragma unroll
;     for (int qt = 0; qt < 2; ++qt) {
;       float ls = lsum[pr][qt];
;       ls += __shfl_xor(ls, 16);
;       ls += __shfl_xor(ls, 32);
;       const float inv = 1.f / ls;
;       const long row = row_base + j0 + w * (32 * QP) + pr * 32 + qt * 16 + l15;
; #pragma unroll
;       for (int dd = 0; dd < 4; ++dd) {
;         u32x2 ov;
;         ov[0] = pack2(o[pr][qt][dd][0] * inv, o[pr][qt][dd][1] * inv);
;         ov[1] = pack2(o[pr][qt][dd][2] * inv, o[pr][qt][dd][3] * inv);
;         *reinterpret_cast<u32x2*>(outp + row * DM + dd * 16 + quad * 4) = ov;
;       }
;     }
	v_add_f32_e32 v13, v13, v14
	v_addc_co_u32_e32 v9, vcc, 0, v5, vcc
	v_div_scale_f32 v14, s[2:3], v13, v13, 1.0
	global_store_dwordx2 v[8:9], v[6:7], off offset:1536
	v_pk_mul_f32 v[6:7], v[40:41], v[2:3] op_sel_hi:[1,0]
	v_pk_mul_f32 v[10:11], v[42:43], v[2:3] op_sel_hi:[1,0]
	v_rcp_f32_e32 v15, v14
	v_cvt_pk_bf16_f32 v6, v6, v7
	v_cvt_pk_bf16_f32 v7, v10, v11
	global_store_dwordx2 v[8:9], v[6:7], off offset:1568
	v_pk_mul_f32 v[6:7], v[44:45], v[2:3] op_sel_hi:[1,0]
	v_pk_mul_f32 v[10:11], v[46:47], v[2:3] op_sel_hi:[1,0]
	ds_bpermute_b32 v1, v1, v210
	v_cvt_pk_bf16_f32 v6, v6, v7
	v_cvt_pk_bf16_f32 v7, v10, v11
	global_store_dwordx2 v[8:9], v[6:7], off offset:1600
	v_pk_mul_f32 v[6:7], v[48:49], v[2:3] op_sel_hi:[1,0]
	v_pk_mul_f32 v[10:11], v[50:51], v[2:3] op_sel_hi:[1,0]
	v_fma_f32 v2, -v14, v15, 1.0
	v_cvt_pk_bf16_f32 v6, v6, v7
	v_cvt_pk_bf16_f32 v7, v10, v11
	v_fmac_f32_e32 v15, v2, v15
	v_div_scale_f32 v2, vcc, 1.0, v13, 1.0
	global_store_dwordx2 v[8:9], v[6:7], off offset:1632
	v_mul_f32_e32 v6, v2, v15
	v_fma_f32 v7, -v14, v6, v2
	s_waitcnt lgkmcnt(0)
	v_add_f32_e32 v1, v210, v1
	v_fmac_f32_e32 v6, v7, v15
	ds_bpermute_b32 v12, v12, v1
	v_fma_f32 v2, -v14, v6, v2
	v_div_fmas_f32 v2, v2, v15, v6
	v_div_fixup_f32 v2, v2, v13, 1.0
	v_pk_mul_f32 v[6:7], v[72:73], v[2:3] op_sel_hi:[1,0]
	v_pk_mul_f32 v[8:9], v[74:75], v[2:3] op_sel_hi:[1,0]
	v_cvt_pk_bf16_f32 v6, v6, v7
	v_cvt_pk_bf16_f32 v7, v8, v9
	v_add_co_u32_e32 v8, vcc, s27, v4
	s_waitcnt lgkmcnt(0)
	v_add_f32_e32 v1, v1, v12
	v_addc_co_u32_e32 v9, vcc, 0, v5, vcc
	v_div_scale_f32 v12, s[2:3], v1, v1, 1.0
	global_store_dwordx2 v[8:9], v[6:7], off offset:1536
	v_pk_mul_f32 v[6:7], v[80:81], v[2:3] op_sel_hi:[1,0]
	v_pk_mul_f32 v[10:11], v[82:83], v[2:3] op_sel_hi:[1,0]
	v_rcp_f32_e32 v13, v12
	v_cvt_pk_bf16_f32 v6, v6, v7
	v_cvt_pk_bf16_f32 v7, v10, v11
	global_store_dwordx2 v[8:9], v[6:7], off offset:1568
	v_pk_mul_f32 v[6:7], v[88:89], v[2:3] op_sel_hi:[1,0]
	v_pk_mul_f32 v[10:11], v[90:91], v[2:3] op_sel_hi:[1,0]
	v_cvt_pk_bf16_f32 v6, v6, v7
	v_cvt_pk_bf16_f32 v7, v10, v11
	global_store_dwordx2 v[8:9], v[6:7], off offset:1600
	v_pk_mul_f32 v[6:7], v[96:97], v[2:3] op_sel_hi:[1,0]
	v_pk_mul_f32 v[10:11], v[98:99], v[2:3] op_sel_hi:[1,0]
	v_fma_f32 v2, -v12, v13, 1.0
	v_cvt_pk_bf16_f32 v6, v6, v7
	v_cvt_pk_bf16_f32 v7, v10, v11
	v_fmac_f32_e32 v13, v2, v13
	v_div_scale_f32 v2, vcc, 1.0, v1, 1.0
	global_store_dwordx2 v[8:9], v[6:7], off offset:1632
	v_mul_f32_e32 v6, v2, v13
	v_fma_f32 v7, -v12, v6, v2
	v_fmac_f32_e32 v6, v7, v13
	v_fma_f32 v2, -v12, v6, v2
	v_div_fmas_f32 v2, v2, v13, v6
	v_div_fixup_f32 v2, v2, v1, 1.0
	v_pk_mul_f32 v[6:7], v[68:69], v[2:3] op_sel_hi:[1,0]
	v_pk_mul_f32 v[8:9], v[70:71], v[2:3] op_sel_hi:[1,0]
	v_add_co_u32_e32 v4, vcc, s28, v4
	v_cvt_pk_bf16_f32 v6, v6, v7
	v_cvt_pk_bf16_f32 v7, v8, v9
	v_addc_co_u32_e32 v5, vcc, 0, v5, vcc
	global_store_dwordx2 v[4:5], v[6:7], off offset:1536
	v_pk_mul_f32 v[6:7], v[76:77], v[2:3] op_sel_hi:[1,0]
	v_pk_mul_f32 v[8:9], v[78:79], v[2:3] op_sel_hi:[1,0]
	v_cvt_pk_bf16_f32 v6, v6, v7
	v_cvt_pk_bf16_f32 v7, v8, v9
	global_store_dwordx2 v[4:5], v[6:7], off offset:1568
	v_pk_mul_f32 v[6:7], v[84:85], v[2:3] op_sel_hi:[1,0]
	v_pk_mul_f32 v[8:9], v[86:87], v[2:3] op_sel_hi:[1,0]
	v_cvt_pk_bf16_f32 v6, v6, v7
	v_cvt_pk_bf16_f32 v7, v8, v9
	global_store_dwordx2 v[4:5], v[6:7], off offset:1600
	v_pk_mul_f32 v[6:7], v[92:93], v[2:3] op_sel_hi:[1,0]
	v_pk_mul_f32 v[8:9], v[94:95], v[2:3] op_sel_hi:[1,0]
	v_cvt_pk_bf16_f32 v6, v6, v7
	v_cvt_pk_bf16_f32 v7, v8, v9
	v_readlane_b32 s41, v251, 59
	v_readlane_b32 s42, v251, 60
	v_readlane_b32 s43, v251, 61
	v_readlane_b32 s44, v251, 62
	v_readlane_b32 s45, v251, 63
	v_readlane_b32 s48, v252, 2
	v_readlane_b32 s49, v252, 3
	v_readlane_b32 s50, v252, 4
	v_readlane_b32 s51, v252, 5
	v_readlane_b32 s52, v252, 6
	v_readlane_b32 s53, v252, 7
	v_readlane_b32 s54, v252, 8
	v_readlane_b32 s55, v252, 9
	global_store_dwordx2 v[4:5], v[6:7], off offset:1632
	s_mov_b64 s[2:3], 0

; DEVI unsigned pack2(float a, float b) { f32x2_t v = {a, b}; bf16x2_t r = __builtin_convertvector(v, bf16x2_t); return *reinterpret_cast<unsigned*>(&r); }
; DEVI float ex2(float x) { return __builtin_amdgcn_exp2f(x); }
; DEVI f32x4 mfma16(bf16x8 a, bf16x8 b, f32x4 c) { return __builtin_amdgcn_mfma_f32_16x16x32_bf16(a, b, c, 0, 0, 0); }
; template <int DK>
; DEVI void attn_tile(const char* kb, const char* vb, const bool first, const bf16x8 (&qf)[2][DK / 32], f32x4 (&o)[2][4],
;                     float (&mrun)[2], float (&lsum)[2], const int l15, const int quad) {
;     ...
;     float ps = 0.f;
; #pragma unroll
;     for (int ks = 0; ks < 4; ++ks)
; #pragma unroll
;       for (int j = 0; j < 4; ++j) { float pv = ex2(s[qt][ks][j]); s[qt][ks][j] = pv; ps += pv; }
;     lsum[qt] += ps;
; #pragma unroll
;     for (int k2 = 0; k2 < 2; ++k2) {
;       u32x4 wv;
;       wv[0] = pack2(s[qt][2 * k2][0], s[qt][2 * k2][1]);
;       wv[1] = pack2(s[qt][2 * k2][2], s[qt][2 * k2][3]);
;       wv[2] = pack2(s[qt][2 * k2 + 1][0], s[qt][2 * k2 + 1][1]);
;       wv[3] = pack2(s[qt][2 * k2 + 1][2], s[qt][2 * k2 + 1][3]);
;       pf[qt][k2] = as_bf8(wv);
;     }
;   }
; #pragma unroll
;   for (int dd = 0; dd < 4; ++dd)
; #pragma unroll
;     for (int k2 = 0; k2 < 2; ++k2) {
;       u32x2 lo = *reinterpret_cast<const u32x2*>(vb + (dd * 16 + l15) * 144 + (k2 * 32 + quad * 4) * 2);
;       u32x2 hi = *reinterpret_cast<const u32x2*>(vb + (dd * 16 + l15) * 144 + (k2 * 32 + 16 + quad * 4) * 2);
;       u32x4 vv = {lo[0], lo[1], hi[0], hi[1]};
;       bf16x8 vf = as_bf8(vv);
;       o[0][dd] = mfma16(vf, pf[0][k2], o[0][dd]);
;       o[1][dd] = mfma16(vf, pf[1][k2], o[1][dd]);
;     }
; template <int DK, int QP>
; DEVI void attn_item(const bf* __restrict__ Q, const bf* __restrict__ Kp, const bf* __restrict__ Vt, bf* __restrict__ outp  ,
;                     long row_base, int j0, int nkeys, char* smem) {
;     ...
;   for (int t = 0; t < nt; ++t) {
;     ALOAD(rkA, rvA, min(t + 1, nt - 1));
;     const char* kb = smem + (t & 1) * STG;
; #pragma unroll
;     for (int pr = 0; pr < QP; ++pr) {
;       attn_tile<DK>(kb, kb + KSZ, t == 0, qf[pr], o[pr], mrun[pr], lsum[pr], l15, quad);
;       if (QP > 1) __builtin_amdgcn_sched_barrier(0);
;     }
;     AWRITE(rkA, rvA, (t + 1) & 1);
;     __syncthreads();
;   }
.LBB0_633:
	v_exp_f32_e32 v112, v88
	v_exp_f32_e32 v113, v89
	v_exp_f32_e32 v114, v90
	v_exp_f32_e32 v115, v91
	v_exp_f32_e32 v116, v92
	v_exp_f32_e32 v117, v93
	v_exp_f32_e32 v118, v94
	v_exp_f32_e32 v119, v95
	v_exp_f32_e32 v120, v80
	v_exp_f32_e32 v121, v81
	v_exp_f32_e32 v122, v82
	v_exp_f32_e32 v123, v83
	v_exp_f32_e32 v136, v84
	v_exp_f32_e32 v137, v85
	v_exp_f32_e32 v138, v86
	v_exp_f32_e32 v139, v87
	v_exp_f32_e32 v108, v108
	v_exp_f32_e32 v109, v109
	v_exp_f32_e32 v110, v110
	v_exp_f32_e32 v111, v111
	v_exp_f32_e32 v104, v104
	v_exp_f32_e32 v105, v105
	v_exp_f32_e32 v106, v106
	v_exp_f32_e32 v107, v107
	v_cvt_pk_bf16_f32 v92, v112, v113
	v_cvt_pk_bf16_f32 v93, v114, v115
	v_cvt_pk_bf16_f32 v94, v116, v117
	v_cvt_pk_bf16_f32 v95, v118, v119
	v_exp_f32_e32 v140, v96
	v_exp_f32_e32 v141, v97
	s_waitcnt lgkmcnt(7)
	v_mfma_f32_16x16x32_bf16 v[84:87], v[56:59], v[92:95], 0
	v_exp_f32_e32 v142, v98
	v_exp_f32_e32 v143, v99
	v_exp_f32_e32 v144, v100
	v_exp_f32_e32 v145, v101
	v_cvt_pk_bf16_f32 v80, v120, v121
	v_cvt_pk_bf16_f32 v81, v122, v123
	v_cvt_pk_bf16_f32 v82, v136, v137
	v_cvt_pk_bf16_f32 v83, v138, v139
	v_exp_f32_e32 v146, v102
	v_exp_f32_e32 v147, v103
	v_cvt_pk_bf16_f32 v88, v108, v109
	v_cvt_pk_bf16_f32 v89, v110, v111
	v_cvt_pk_bf16_f32 v90, v104, v105
	v_cvt_pk_bf16_f32 v91, v106, v107
	v_mfma_f32_16x16x32_bf16 v[96:99], v[56:59], v[80:83], 0
	v_cvt_pk_bf16_f32 v100, v140, v141
	v_cvt_pk_bf16_f32 v101, v142, v143
	v_cvt_pk_bf16_f32 v102, v144, v145
	s_waitcnt lgkmcnt(6)
	v_mfma_f32_16x16x32_bf16 v[56:59], v[32:35], v[88:91], v[84:87]
	v_cvt_pk_bf16_f32 v103, v146, v147
	s_waitcnt vmcnt(4)
	ds_write_b128 v132, v[60:63] offset:23552
	s_waitcnt vmcnt(3)
	ds_write_b128 v133, v[64:67] offset:23552
	s_waitcnt vmcnt(2)
	ds_write_b128 v134, v[68:71] offset:23552
	s_waitcnt vmcnt(1)
	ds_write_b128 v135, v[72:75] offset:37888
	s_waitcnt vmcnt(0)
	ds_write_b128 v135, v[76:79] offset:42496
	v_add_f32_e32 v60, 0, v120
	s_waitcnt lgkmcnt(10)
	v_mfma_f32_16x16x32_bf16 v[84:87], v[48:51], v[92:95], 0
	v_add_f32_e32 v60, v121, v60
	v_add_f32_e32 v60, v122, v60
	v_add_f32_e32 v60, v123, v60
	v_mfma_f32_16x16x32_bf16 v[32:35], v[32:35], v[100:103], v[96:99]
	v_add_f32_e32 v60, v136, v60
	v_add_f32_e32 v60, v137, v60
	v_add_f32_e32 v60, v138, v60
	v_mfma_f32_16x16x32_bf16 v[96:99], v[48:51], v[80:83], 0
	v_add_f32_e32 v60, v139, v60
	v_add_f32_e32 v60, v140, v60
	v_add_f32_e32 v60, v141, v60
	s_waitcnt lgkmcnt(9)
	v_mfma_f32_16x16x32_bf16 v[48:51], v[28:31], v[88:91], v[84:87]
	v_add_f32_e32 v60, v142, v60
	v_add_f32_e32 v60, v143, v60
	s_mov_b32 s17, 0x8200
	v_add_f32_e32 v84, 0, v112
	v_add_f32_e32 v84, v113, v84
	v_add_f32_e32 v84, v114, v84
	v_mfma_f32_16x16x32_bf16 v[28:31], v[28:31], v[100:103], v[96:99]
	v_add_f32_e32 v60, v144, v60
	v_mad_i64_i32 v[168:169], s[10:11], v130, s17, 0
	s_nop 0
	v_add_f32_e32 v96, v115, v84
	v_add_f32_e32 v96, v116, v96
	v_add_f32_e32 v96, v117, v96
	s_waitcnt lgkmcnt(8)
	v_mfma_f32_16x16x32_bf16 v[84:87], v[44:47], v[92:95], 0
	v_add_f32_e32 v112, v118, v96
	v_mad_i64_i32 v[170:171], s[10:11], v131, s17, 0
	v_mfma_f32_16x16x32_bf16 v[96:99], v[44:47], v[80:83], 0
	v_add_f32_e32 v44, v119, v112
	v_add_f32_e32 v44, v108, v44
	v_add_f32_e32 v108, v109, v44
	s_waitcnt lgkmcnt(7)
	v_mfma_f32_16x16x32_bf16 v[44:47], v[36:39], v[88:91], v[84:87]
	v_add_f32_e32 v60, v145, v60
	s_movk_i32 s11, 0x90
	v_add_f32_e32 v60, v146, v60
	v_add_f32_e32 v84, v110, v108
	v_add_f32_e32 v84, v111, v84
	v_add_f32_e32 v84, v104, v84
	v_add_f32_e32 v84, v105, v84
	v_add_f32_e32 v84, v106, v84
	v_mfma_f32_16x16x32_bf16 v[36:39], v[36:39], v[100:103], v[96:99]
	v_add_f32_e32 v60, v147, v60
	s_add_i32 s10, s24, -1
	v_add_u32_e32 v209, 0xe00, v208
	v_add_f32_e32 v96, v107, v84
	s_waitcnt lgkmcnt(6)
	v_mfma_f32_16x16x32_bf16 v[84:87], v[52:55], v[92:95], 0
	v_add_f32_e32 v166, 0, v96
	v_add_u32_e32 v210, 0x1c00, v208
	v_add_u32_e32 v211, 0x2a00, v208
	v_mfma_f32_16x16x32_bf16 v[80:83], v[52:55], v[80:83], 0
	v_mul_u32_u24_e32 v212, 0x90, v158
	v_mad_u32_u24 v213, v158, s11, v191
	v_add_f32_e32 v153, 0, v60
	s_waitcnt lgkmcnt(5)
	v_mfma_f32_16x16x32_bf16 v[52:55], v[40:43], v[88:91], v[84:87]
	v_lshl_add_u64 v[172:173], v[124:125], 1, s[12:13]
	v_lshl_add_u64 v[174:175], v[126:127], 1, s[12:13]
	v_lshl_add_u64 v[176:177], v[128:129], 1, s[12:13]
	v_mfma_f32_16x16x32_bf16 v[40:43], v[40:43], v[100:103], v[80:83]
	v_mov_b32_e32 v84, 0x1200
	v_mad_u32_u24 v214, v158, s11, v84
	v_mov_b32_e32 v84, 0x1b00
	v_mad_u32_u24 v215, v158, s11, v84
	s_mov_b32 s11, 1
	s_waitcnt lgkmcnt(0)
	s_barrier
	v_add_u32_e32 v209, v208, v2
	v_mul_u32_u24_e32 v210, 0x90, v158
	v_add_u32_e32 v210, v210, v156
	v_add_u32_e32 v210, 0x3800, v210
	v_add_u32_e32 v211, v161, v165
	v_add_u32_e32 v212, v167, v204
	v_add_u32_e32 v213, v205, v206
	v_add_u32_e32 v214, v160, v207
	v_lshlrev_b32_e32 v215, 4, v178
	v_add_u32_e32 v174, v160, v168
	v_add_u32_e32 v175, v160, v170
	v_readfirstlane_b32 s22, v162
	v_readfirstlane_b32 s23, v163
	v_add_u32_e32 v172, 0x1000, v215
	v_add_u32_e32 v173, 0x2000, v215
	s_add_u32 s12, s12, 0x6000
	s_addc_u32 s13, s13, 0
	s_add_u32 s22, s22, 0x100
	s_addc_u32 s23, s23, 0
	s_mov_b32 s18, 0x5c00
	s_mov_b32 s17, 0x41000000
	v_xor_b32_e32 v140, 0x80000000, v164
	v_mov_b32_e32 v141, v140
	v_mov_b32_e32 v142, v140
	v_mov_b32_e32 v143, v140
	v_xor_b32_e32 v216, 0x80000000, v1
	v_mov_b32_e32 v217, v216
	v_mov_b32_e32 v218, v216
	v_mov_b32_e32 v219, v216
	s_nop 4
; DEVI float ex2(float x) { return __builtin_amdgcn_exp2f(x); }
; DEVI f32x4 mfma16(bf16x8 a, bf16x8 b, f32x4 c) { return __builtin_amdgcn_mfma_f32_16x16x32_bf16(a, b, c, 0, 0, 0); }
; template <int DK>
; DEVI void attn_tile(const char* kb, const char* vb, const bool first, const bf16x8 (&qf)[2][DK / 32], f32x4 (&o)[2][4],
;                     float (&mrun)[2], float (&lsum)[2], const int l15, const int quad) {
;     ...
;   f32x4 s[2][4];
; #pragma unroll
;   for (int qt = 0; qt < 2; ++qt)
; #pragma unroll
;     for (int ks = 0; ks < 4; ++ks) { const float nm = -mrun[qt]; s[qt][ks] = f32x4{nm, nm, nm, nm}; }
; #pragma unroll
;   for (int ks = 0; ks < 4; ++ks)
; #pragma unroll
;     for (int kk = 0; kk < NKK; ++kk) {
;       bf16x8 kf = *reinterpret_cast<const bf16x8*>(kb + (ks * 16 + l15) * KSTR + (kk * 32 + quad * 8) * 2);
;       s[0][ks] = mfma16(kf, qf[0][kk], s[0][ks]);
;       s[1][ks] = mfma16(kf, qf[1][kk], s[1][ks]);
;     }
;   bf16x8 pf[2][2];
; #pragma unroll
;   for (int qt = 0; qt < 2; ++qt) {
;     float mx = fmaxf(fmaxf(s[qt][0][0], s[qt][0][1]), fmaxf(s[qt][0][2], s[qt][0][3]));
; #pragma unroll
;     for (int ks = 1; ks < 4; ++ks) mx = fmaxf(mx, fmaxf(fmaxf(s[qt][ks][0], s[qt][ks][1]), fmaxf(s[qt][ks][2], s[qt][ks][3])));
;     if (__any(first || (mx > 8.f))) {
;       float rm = fmaxf(mx, __shfl_xor(mx, 16));
;       rm = fmaxf(rm, __shfl_xor(rm, 32));
;       const float delta = first ? rm : fmaxf(rm, 0.f);
;       const float alpha = first ? 1.f : ex2(-delta);
;       mrun[qt] += delta;
;       lsum[qt] *= alpha;
; #pragma unroll
;       for (int ks = 0; ks < 4; ++ks)
; #pragma unroll
;         for (int j = 0; j < 4; ++j) s[qt][ks][j] -= delta;
; #pragma unroll
;       for (int dd = 0; dd < 4; ++dd)
; #pragma unroll
;         for (int j = 0; j < 4; ++j) o[qt][dd][j] *= alpha;
;     }
;     float ps = 0.f;
; #pragma unroll
;     for (int ks = 0; ks < 4; ++ks)
; #pragma unroll
;       for (int j = 0; j < 4; ++j) { float pv = ex2(s[qt][ks][j]); s[qt][ks][j] = pv; ps += pv; }
;     lsum[qt] += ps;
.Lmla_loop_a:
	v_add_u32_e32 v148, s18, v209
	global_load_dwordx4 v[224:227], v215, s[12:13]
	global_load_dwordx4 v[228:231], v172, s[12:13]
	global_load_dwordx4 v[232:235], v173, s[12:13]
	ds_read_b128 v[60:63], v148
	ds_read_b128 v[64:67], v148 offset:64
	ds_read_b128 v[68:71], v148 offset:128
	global_load_dwordx4 v[168:171], v174, s[22:23]
	global_load_dwordx4 v[160:163], v175, s[22:23]
	ds_read_b128 v[72:75], v148 offset:3584
	ds_read_b128 v[76:79], v148 offset:3648
	ds_read_b128 v[80:83], v148 offset:3712
	ds_read_b128 v[84:87], v148 offset:7168
	ds_read_b128 v[88:91], v148 offset:7232
	ds_read_b128 v[92:95], v148 offset:7296
	ds_read_b128 v[96:99], v148 offset:10752
	ds_read_b128 v[100:103], v148 offset:10816
	ds_read_b128 v[104:107], v148 offset:10880
	s_add_i32 s96, s11, 2
	s_cmp_lt_i32 s96, s24
	s_cselect_b32 s96, 0x3000, 0
	s_add_u32 s12, s12, s96
	s_addc_u32 s13, s13, 0
	s_lshr_b32 s96, s96, 12
	s_cmp_lg_u32 s96, 0
	s_cselect_b32 s96, 0x80, 0
	s_add_u32 s22, s22, s96
	s_addc_u32 s23, s23, 0
	s_waitcnt lgkmcnt(11)
	v_mfma_f32_16x16x32_bf16 v[108:111], v[60:63], v[4:7], v[140:143]
	s_waitcnt lgkmcnt(10)
	v_mfma_f32_16x16x32_bf16 v[108:111], v[64:67], v[8:11], v[108:111]
	s_waitcnt lgkmcnt(9)
	v_mfma_f32_16x16x32_bf16 v[108:111], v[68:71], v[12:15], v[108:111]
	s_waitcnt lgkmcnt(8)
	v_mfma_f32_16x16x32_bf16 v[112:115], v[72:75], v[4:7], v[140:143]
	s_waitcnt lgkmcnt(7)
	v_mfma_f32_16x16x32_bf16 v[112:115], v[76:79], v[8:11], v[112:115]
	s_waitcnt lgkmcnt(6)
	v_mfma_f32_16x16x32_bf16 v[112:115], v[80:83], v[12:15], v[112:115]
	s_waitcnt lgkmcnt(5)
	v_mfma_f32_16x16x32_bf16 v[116:119], v[84:87], v[4:7], v[140:143]
	s_waitcnt lgkmcnt(4)
	v_mfma_f32_16x16x32_bf16 v[116:119], v[88:91], v[8:11], v[116:119]
	s_waitcnt lgkmcnt(3)
	v_mfma_f32_16x16x32_bf16 v[116:119], v[92:95], v[12:15], v[116:119]
	s_waitcnt lgkmcnt(2)
	v_mfma_f32_16x16x32_bf16 v[120:123], v[96:99], v[4:7], v[140:143]
	s_waitcnt lgkmcnt(1)
	v_mfma_f32_16x16x32_bf16 v[120:123], v[100:103], v[8:11], v[120:123]
	s_waitcnt lgkmcnt(0)
	v_mfma_f32_16x16x32_bf16 v[120:123], v[104:107], v[12:15], v[120:123]
	v_mfma_f32_16x16x32_bf16 v[124:127], v[60:63], v[16:19], v[216:219]
	v_mfma_f32_16x16x32_bf16 v[124:127], v[64:67], v[20:23], v[124:127]
	v_max3_f32 v150, v108, v109, v110
	v_max3_f32 v151, v111, v112, v113
	v_mfma_f32_16x16x32_bf16 v[124:127], v[68:71], v[24:27], v[124:127]
	v_max3_f32 v176, v114, v115, v116
	v_max3_f32 v177, v117, v118, v119
	v_mfma_f32_16x16x32_bf16 v[128:131], v[72:75], v[16:19], v[216:219]
	s_nop 0
	v_max3_f32 v150, v150, v151, v120
	v_max3_f32 v176, v176, v177, v121
	v_mfma_f32_16x16x32_bf16 v[128:131], v[76:79], v[20:23], v[128:131]
	v_max3_f32 v150, v150, v176, v122
	v_max_f32_e32 v150, v150, v123
	v_cmp_lt_f32_e32 vcc, s17, v150
	s_cbranch_vccnz .Lmla_rare0_a
.Lmla_join0_a:
	v_mfma_f32_16x16x32_bf16 v[128:131], v[80:83], v[24:27], v[128:131]
	v_add_u32_e32 v149, s18, v210
	ds_read_b64 v[60:61], v149 offset:0
	ds_read_b64 v[62:63], v149 offset:32
	ds_read_b64 v[64:65], v149 offset:2304
	ds_read_b64 v[66:67], v149 offset:2336
	ds_read_b64 v[68:69], v149 offset:4608
	ds_read_b64 v[70:71], v149 offset:4640
	ds_read_b64 v[72:73], v149 offset:6912
	ds_read_b64 v[74:75], v149 offset:6944
	v_exp_f32_e32 v108, v108
	v_exp_f32_e32 v109, v109
	v_exp_f32_e32 v110, v110
	v_exp_f32_e32 v111, v111
	v_add_f32_e32 v151, v108, v109
	v_mfma_f32_16x16x32_bf16 v[132:135], v[84:87], v[16:19], v[216:219]
	v_exp_f32_e32 v112, v112
	v_add_f32_e32 v176, v110, v111
	v_exp_f32_e32 v113, v113
	v_exp_f32_e32 v114, v114
	v_add_f32_e32 v151, v151, v112
	v_exp_f32_e32 v115, v115
	v_mfma_f32_16x16x32_bf16 v[132:135], v[88:91], v[20:23], v[132:135]
	v_add_f32_e32 v176, v176, v113
	v_exp_f32_e32 v116, v116
	v_add_f32_e32 v151, v151, v114
	v_exp_f32_e32 v117, v117
	v_add_f32_e32 v176, v176, v115
	v_exp_f32_e32 v118, v118
	ds_read_b64 v[76:77], v149 offset:64
	ds_read_b64 v[78:79], v149 offset:96
	ds_read_b64 v[80:81], v149 offset:2368
	ds_read_b64 v[82:83], v149 offset:2400
	ds_read_b64 v[84:85], v149 offset:4672
	ds_read_b64 v[86:87], v149 offset:4704
	ds_read_b64 v[88:89], v149 offset:6976
	ds_read_b64 v[90:91], v149 offset:7008
	v_mfma_f32_16x16x32_bf16 v[132:135], v[92:95], v[24:27], v[132:135]
	v_add_f32_e32 v151, v151, v116
	v_exp_f32_e32 v119, v119
	v_add_f32_e32 v176, v176, v117
	v_exp_f32_e32 v120, v120
	v_add_f32_e32 v151, v151, v118
	v_mfma_f32_16x16x32_bf16 v[136:139], v[96:99], v[16:19], v[216:219]
	v_exp_f32_e32 v121, v121
	v_add_f32_e32 v176, v176, v119
	v_exp_f32_e32 v122, v122
	v_add_f32_e32 v151, v151, v120
	v_exp_f32_e32 v123, v123
	v_add_f32_e32 v176, v176, v121
	v_mfma_f32_16x16x32_bf16 v[136:139], v[100:103], v[20:23], v[136:139]
	v_add_f32_e32 v151, v151, v122
	v_add_f32_e32 v176, v176, v123
	v_add_f32_e32 v151, v151, v176
	v_add_f32_e32 v166, v166, v151
	v_cvt_pk_bf16_f32 v140, v108, v109
	v_cvt_pk_bf16_f32 v141, v110, v111
	v_mfma_f32_16x16x32_bf16 v[136:139], v[104:107], v[24:27], v[136:139]
	v_cvt_pk_bf16_f32 v142, v112, v113
	v_cvt_pk_bf16_f32 v143, v114, v115
	v_cvt_pk_bf16_f32 v144, v116, v117
	v_cvt_pk_bf16_f32 v145, v118, v119
	v_cvt_pk_bf16_f32 v146, v120, v121
	v_cvt_pk_bf16_f32 v147, v122, v123
	s_waitcnt lgkmcnt(14)
	v_mfma_f32_16x16x32_bf16 v[56:59], v[60:63], v[140:143], v[56:59]
	v_max3_f32 v150, v124, v125, v126
	v_max3_f32 v151, v127, v128, v129
	s_waitcnt lgkmcnt(12)
	v_mfma_f32_16x16x32_bf16 v[48:51], v[64:67], v[140:143], v[48:51]
	v_max3_f32 v176, v130, v131, v132
	v_max3_f32 v177, v133, v134, v135
	v_max3_f32 v150, v150, v151, v136
	v_max3_f32 v176, v176, v177, v137
	s_waitcnt lgkmcnt(10)
	v_mfma_f32_16x16x32_bf16 v[44:47], v[68:71], v[140:143], v[44:47]
	v_max3_f32 v150, v150, v176, v138
	v_max_f32_e32 v150, v150, v139
	v_cmp_lt_f32_e32 vcc, s17, v150
	s_cbranch_vccnz .Lmla_rare1_a
; DEVI unsigned pack2(float a, float b) { f32x2_t v = {a, b}; bf16x2_t r = __builtin_convertvector(v, bf16x2_t); return *reinterpret_cast<unsigned*>(&r); }
; template <int DK>
; DEVI void attn_tile(const char* kb, const char* vb, const bool first, const bf16x8 (&qf)[2][DK / 32], f32x4 (&o)[2][4],
;                     float (&mrun)[2], float (&lsum)[2], const int l15, const int quad) {
;     ...
;     if (__any(first || (mx > 8.f))) {
;       float rm = fmaxf(mx, __shfl_xor(mx, 16));
;       rm = fmaxf(rm, __shfl_xor(rm, 32));
;       const float delta = first ? rm : fmaxf(rm, 0.f);
;       const float alpha = first ? 1.f : ex2(-delta);
;       mrun[qt] += delta;
;       lsum[qt] *= alpha;
; #pragma unroll
;       for (int ks = 0; ks < 4; ++ks)
; #pragma unroll
;         for (int j = 0; j < 4; ++j) s[qt][ks][j] -= delta;
; #pragma unroll
;       for (int dd = 0; dd < 4; ++dd)
; #pragma unroll
;         for (int j = 0; j < 4; ++j) o[qt][dd][j] *= alpha;
;     }
;     float ps = 0.f;
; #pragma unroll
;     for (int ks = 0; ks < 4; ++ks)
; #pragma unroll
;       for (int j = 0; j < 4; ++j) { float pv = ex2(s[qt][ks][j]); s[qt][ks][j] = pv; ps += pv; }
;     lsum[qt] += ps;
; #pragma unroll
;     for (int k2 = 0; k2 < 2; ++k2) {
;       u32x4 wv;
;       wv[0] = pack2(s[qt][2 * k2][0], s[qt][2 * k2][1]);
;       wv[1] = pack2(s[qt][2 * k2][2], s[qt][2 * k2][3]);
;       wv[2] = pack2(s[qt][2 * k2 + 1][0], s[qt][2 * k2 + 1][1]);
;       wv[3] = pack2(s[qt][2 * k2 + 1][2], s[qt][2 * k2 + 1][3]);
;       pf[qt][k2] = as_bf8(wv);
;     }
;   }
; #pragma unroll
;   for (int dd = 0; dd < 4; ++dd)
; #pragma unroll
;     for (int k2 = 0; k2 < 2; ++k2) {
;       u32x2 lo = *reinterpret_cast<const u32x2*>(vb + (dd * 16 + l15) * 144 + (k2 * 32 + quad * 4) * 2);
;       u32x2 hi = *reinterpret_cast<const u32x2*>(vb + (dd * 16 + l15) * 144 + (k2 * 32 + 16 + quad * 4) * 2);
;       u32x4 vv = {lo[0], lo[1], hi[0], hi[1]};
;       bf16x8 vf = as_bf8(vv);
;       o[0][dd] = mfma16(vf, pf[0][k2], o[0][dd]);
;       o[1][dd] = mfma16(vf, pf[1][k2], o[1][dd]);
;     }
; template <int DK, int QP>
; DEVI void attn_item(const bf* __restrict__ Q, const bf* __restrict__ Kp, const bf* __restrict__ Vt, bf* __restrict__ outp  ,
;                     long row_base, int j0, int nkeys, char* smem) {
;     ...
;     AWRITE(rkA, rvA, (t + 1) & 1);
;     __syncthreads();
.Lmla_join1_a:
	s_waitcnt lgkmcnt(8)
	v_mfma_f32_16x16x32_bf16 v[52:55], v[72:75], v[140:143], v[52:55]
	v_exp_f32_e32 v124, v124
	v_exp_f32_e32 v125, v125
	v_exp_f32_e32 v126, v126
	v_exp_f32_e32 v127, v127
	v_add_f32_e32 v151, v124, v125
	v_exp_f32_e32 v128, v128
	v_add_f32_e32 v176, v126, v127
	v_exp_f32_e32 v129, v129
	s_waitcnt lgkmcnt(6)
	v_mfma_f32_16x16x32_bf16 v[56:59], v[76:79], v[144:147], v[56:59]
	v_exp_f32_e32 v130, v130
	v_add_f32_e32 v151, v151, v128
	v_exp_f32_e32 v131, v131
	v_add_f32_e32 v176, v176, v129
	v_exp_f32_e32 v132, v132
	v_add_f32_e32 v151, v151, v130
	v_exp_f32_e32 v133, v133
	v_add_f32_e32 v176, v176, v131
	s_waitcnt lgkmcnt(4)
	v_mfma_f32_16x16x32_bf16 v[48:51], v[80:83], v[144:147], v[48:51]
	v_exp_f32_e32 v134, v134
	v_add_f32_e32 v151, v151, v132
	v_exp_f32_e32 v135, v135
	v_add_f32_e32 v176, v176, v133
	v_exp_f32_e32 v136, v136
	v_add_f32_e32 v151, v151, v134
	v_exp_f32_e32 v137, v137
	v_add_f32_e32 v176, v176, v135
	s_waitcnt lgkmcnt(2)
	v_mfma_f32_16x16x32_bf16 v[44:47], v[84:87], v[144:147], v[44:47]
	v_exp_f32_e32 v138, v138
	v_add_f32_e32 v151, v151, v136
	v_exp_f32_e32 v139, v139
	v_add_f32_e32 v176, v176, v137
	v_add_f32_e32 v151, v151, v138
	v_add_f32_e32 v176, v176, v139
	v_add_f32_e32 v151, v151, v176
	v_add_f32_e32 v153, v153, v151
	s_waitcnt lgkmcnt(0)
	v_mfma_f32_16x16x32_bf16 v[52:55], v[88:91], v[144:147], v[52:55]
	v_cvt_pk_bf16_f32 v216, v124, v125
	v_cvt_pk_bf16_f32 v217, v126, v127
	v_cvt_pk_bf16_f32 v218, v128, v129
	v_cvt_pk_bf16_f32 v219, v130, v131
	v_cvt_pk_bf16_f32 v220, v132, v133
	v_cvt_pk_bf16_f32 v221, v134, v135
	v_cvt_pk_bf16_f32 v222, v136, v137
	v_cvt_pk_bf16_f32 v223, v138, v139
	s_xor_b32 s18, s18, 0x5c00
	s_nop 0
	v_mfma_f32_16x16x32_bf16 v[32:35], v[60:63], v[216:219], v[32:35]
	v_mfma_f32_16x16x32_bf16 v[28:31], v[64:67], v[216:219], v[28:31]
	v_xor_b32_e32 v140, 0x80000000, v164
	v_mov_b32_e32 v141, v140
	v_mfma_f32_16x16x32_bf16 v[36:39], v[68:71], v[216:219], v[36:39]
	v_mov_b32_e32 v142, v140
	v_mov_b32_e32 v143, v140
	v_mfma_f32_16x16x32_bf16 v[40:43], v[72:75], v[216:219], v[40:43]
	v_add_u32_e32 v150, s18, v211
	s_waitcnt vmcnt(4)
	ds_write_b128 v150, v[224:227]
	v_mfma_f32_16x16x32_bf16 v[32:35], v[76:79], v[220:223], v[32:35]
	v_add_u32_e32 v151, s18, v212
	s_waitcnt vmcnt(3)
	ds_write_b128 v151, v[228:231]
	v_mfma_f32_16x16x32_bf16 v[28:31], v[80:83], v[220:223], v[28:31]
	v_add_u32_e32 v150, s18, v213
	s_waitcnt vmcnt(2)
	ds_write_b128 v150, v[232:235]
	v_mfma_f32_16x16x32_bf16 v[36:39], v[84:87], v[220:223], v[36:39]
	v_add_u32_e32 v151, s18, v214
	s_waitcnt vmcnt(1)
	ds_write_b128 v151, v[168:171] offset:14336
	v_mfma_f32_16x16x32_bf16 v[40:43], v[88:91], v[220:223], v[40:43]
	s_waitcnt vmcnt(0)
	ds_write_b128 v151, v[160:163] offset:18944
	v_xor_b32_e32 v216, 0x80000000, v1
	v_mov_b32_e32 v217, v216
	v_mov_b32_e32 v218, v216
	v_mov_b32_e32 v219, v216
	s_add_i32 s11, s11, 1
	s_cmp_lg_u32 s11, s24
	s_waitcnt lgkmcnt(0)
	s_barrier
	s_cbranch_scc1 .Lmla_loop_a
	s_branch .Lmla_exit_a
.Lmla_rare0_a:
	v_cmp_lt_i32_e32 vcc, v186, v184
	s_nop 1
	v_cndmask_b32_e32 v151, v183, v186, vcc
	v_lshlrev_b32_e32 v151, 2, v151
	ds_bpermute_b32 v151, v151, v150
	v_cmp_lt_i32_e32 vcc, v185, v184
	s_waitcnt lgkmcnt(0)
	v_max_f32_e32 v150, v150, v151
	v_cndmask_b32_e32 v151, v183, v185, vcc
	v_lshlrev_b32_e32 v151, 2, v151
	ds_bpermute_b32 v151, v151, v150
	s_waitcnt lgkmcnt(0)
	v_max3_f32 v150, v150, v151, 0
	v_exp_f32_e64 v176, -v150
	v_add_f32_e32 v164, v164, v150
	v_sub_f32_e32 v108, v108, v150
	v_sub_f32_e32 v109, v109, v150
	v_sub_f32_e32 v110, v110, v150
	v_sub_f32_e32 v111, v111, v150
	v_sub_f32_e32 v112, v112, v150
	v_sub_f32_e32 v113, v113, v150
	v_sub_f32_e32 v114, v114, v150
	v_sub_f32_e32 v115, v115, v150
	v_sub_f32_e32 v116, v116, v150
	v_sub_f32_e32 v117, v117, v150
	v_sub_f32_e32 v118, v118, v150
	v_sub_f32_e32 v119, v119, v150
	v_sub_f32_e32 v120, v120, v150
	v_sub_f32_e32 v121, v121, v150
	v_sub_f32_e32 v122, v122, v150
	v_sub_f32_e32 v123, v123, v150
	v_mul_f32_e32 v166, v166, v176
	v_mul_f32_e32 v56, v56, v176
	v_mul_f32_e32 v57, v57, v176
	v_mul_f32_e32 v58, v58, v176
	v_mul_f32_e32 v59, v59, v176
	v_mul_f32_e32 v48, v48, v176
	v_mul_f32_e32 v49, v49, v176
	v_mul_f32_e32 v50, v50, v176
	v_mul_f32_e32 v51, v51, v176
	v_mul_f32_e32 v44, v44, v176
	v_mul_f32_e32 v45, v45, v176
	v_mul_f32_e32 v46, v46, v176
	v_mul_f32_e32 v47, v47, v176
	v_mul_f32_e32 v52, v52, v176
	v_mul_f32_e32 v53, v53, v176
	v_mul_f32_e32 v54, v54, v176
	v_mul_f32_e32 v55, v55, v176
	s_branch .Lmla_join0_a
; DEVI unsigned pack2(float a, float b) { f32x2_t v = {a, b}; bf16x2_t r = __builtin_convertvector(v, bf16x2_t); return *reinterpret_cast<unsigned*>(&r); }
; DEVI float ex2(float x) { return __builtin_amdgcn_exp2f(x); }
; template <int DK>
; DEVI void attn_tile(const char* kb, const char* vb, const bool first, const bf16x8 (&qf)[2][DK / 32], f32x4 (&o)[2][4],
;                     float (&mrun)[2], float (&lsum)[2], const int l15, const int quad) {
;     ...
;     if (__any(first || (mx > 8.f))) {
;       float rm = fmaxf(mx, __shfl_xor(mx, 16));
;       rm = fmaxf(rm, __shfl_xor(rm, 32));
;       const float delta = first ? rm : fmaxf(rm, 0.f);
;       const float alpha = first ? 1.f : ex2(-delta);
;       mrun[qt] += delta;
;       lsum[qt] *= alpha;
; #pragma unroll
;       for (int ks = 0; ks < 4; ++ks)
; #pragma unroll
;         for (int j = 0; j < 4; ++j) s[qt][ks][j] -= delta;
; #pragma unroll
;       for (int dd = 0; dd < 4; ++dd)
; #pragma unroll
;         for (int j = 0; j < 4; ++j) o[qt][dd][j] *= alpha;
;     }
; template <int DK, int QP>
; DEVI void attn_item(const bf* __restrict__ Q, const bf* __restrict__ Kp, const bf* __restrict__ Vt, bf* __restrict__ outp  ,
;                     long row_base, int j0, int nkeys, char* smem) {
;     ...
; #pragma unroll
;   for (int pr = 0; pr < QP; ++pr)
; #pragma unroll
;     for (int qt = 0; qt < 2; ++qt) {
;       float ls = lsum[pr][qt];
;       ls += __shfl_xor(ls, 16);
;       ls += __shfl_xor(ls, 32);
;       const float inv = 1.f / ls;
;       const long row = row_base + j0 + w * (32 * QP) + pr * 32 + qt * 16 + l15;
; #pragma unroll
;       for (int dd = 0; dd < 4; ++dd) {
;         u32x2 ov;
;         ov[0] = pack2(o[pr][qt][dd][0] * inv, o[pr][qt][dd][1] * inv);
;         ov[1] = pack2(o[pr][qt][dd][2] * inv, o[pr][qt][dd][3] * inv);
;         *reinterpret_cast<u32x2*>(outp + row * DM + dd * 16 + quad * 4) = ov;
;       }
;     }
.Lmla_rare1_a:
	v_cmp_lt_i32_e32 vcc, v186, v184
	s_nop 1
	v_cndmask_b32_e32 v151, v183, v186, vcc
	v_lshlrev_b32_e32 v151, 2, v151
	ds_bpermute_b32 v151, v151, v150
	v_cmp_lt_i32_e32 vcc, v185, v184
	s_waitcnt lgkmcnt(0)
	v_max_f32_e32 v150, v150, v151
	v_cndmask_b32_e32 v151, v183, v185, vcc
	v_lshlrev_b32_e32 v151, 2, v151
	ds_bpermute_b32 v151, v151, v150
	s_waitcnt lgkmcnt(0)
	v_max3_f32 v150, v150, v151, 0
	v_exp_f32_e64 v176, -v150
	v_add_f32_e32 v1, v1, v150
	v_sub_f32_e32 v124, v124, v150
	v_sub_f32_e32 v125, v125, v150
	v_sub_f32_e32 v126, v126, v150
	v_sub_f32_e32 v127, v127, v150
	v_sub_f32_e32 v128, v128, v150
	v_sub_f32_e32 v129, v129, v150
	v_sub_f32_e32 v130, v130, v150
	v_sub_f32_e32 v131, v131, v150
	v_sub_f32_e32 v132, v132, v150
	v_sub_f32_e32 v133, v133, v150
	v_sub_f32_e32 v134, v134, v150
	v_sub_f32_e32 v135, v135, v150
	v_sub_f32_e32 v136, v136, v150
	v_sub_f32_e32 v137, v137, v150
	v_sub_f32_e32 v138, v138, v150
	v_sub_f32_e32 v139, v139, v150
	v_mul_f32_e32 v153, v153, v176
	v_mul_f32_e32 v32, v32, v176
	v_mul_f32_e32 v33, v33, v176
	v_mul_f32_e32 v34, v34, v176
	v_mul_f32_e32 v35, v35, v176
	v_mul_f32_e32 v28, v28, v176
	v_mul_f32_e32 v29, v29, v176
	v_mul_f32_e32 v30, v30, v176
	v_mul_f32_e32 v31, v31, v176
	v_mul_f32_e32 v36, v36, v176
	v_mul_f32_e32 v37, v37, v176
	v_mul_f32_e32 v38, v38, v176
	v_mul_f32_e32 v39, v39, v176
	v_mul_f32_e32 v40, v40, v176
	v_mul_f32_e32 v41, v41, v176
	v_mul_f32_e32 v42, v42, v176
	v_mul_f32_e32 v43, v43, v176
	s_branch .Lmla_join1_a
.Lmla_exit_a:
.LBB0_640:
	v_cmp_lt_i32_e32 vcc, v186, v184
	v_readlane_b32 s40, v251, 58
	s_lshl_b32 s10, s21, 7
	v_cndmask_b32_e32 v1, v183, v186, vcc
	v_lshlrev_b32_e32 v1, 2, v1
	ds_bpermute_b32 v2, v1, v166
	v_cmp_lt_i32_e32 vcc, v185, v184
	v_readlane_b32 s46, v252, 0
	v_readlane_b32 s47, v252, 1
	v_cndmask_b32_e32 v4, v183, v185, vcc
	v_lshlrev_b32_e32 v10, 2, v4
	s_waitcnt lgkmcnt(0)
	v_add_f32_e32 v2, v166, v2
	ds_bpermute_b32 v6, v10, v2
	s_add_u32 s10, s46, s10
	s_mulk_i32 s3, 0x4100
	s_addc_u32 s11, s47, 0
	s_ashr_i32 s12, s3, 31
	s_add_u32 s2, s3, s2
	s_addc_u32 s3, s12, 0
	v_mov_b32_e32 v159, v3
	s_waitcnt lgkmcnt(0)
	v_add_f32_e32 v2, v2, v6
	v_lshl_add_u64 v[4:5], s[2:3], 0, v[158:159]
	v_div_scale_f32 v8, s[2:3], v2, v2, 1.0
	v_rcp_f32_e32 v9, v8
	ds_bpermute_b32 v1, v1, v153
	v_ashrrev_i32_e32 v155, 31, v154
	v_lshl_add_u64 v[4:5], v[4:5], 0, v[154:155]
	v_fma_f32 v11, -v8, v9, 1.0
	v_fmac_f32_e32 v9, v11, v9
	v_div_scale_f32 v11, vcc, 1.0, v2, 1.0
	v_mul_f32_e32 v12, v11, v9
	s_waitcnt lgkmcnt(0)
	v_add_f32_e32 v1, v153, v1
	v_fma_f32 v13, -v8, v12, v11
	ds_bpermute_b32 v10, v10, v1
	v_fmac_f32_e32 v12, v13, v9
	v_fma_f32 v8, -v8, v12, v11
	v_mov_b32_e32 v157, v3
	v_div_fmas_f32 v8, v8, v9, v12
	v_lshl_add_u64 v[6:7], s[10:11], 0, v[156:157]
	v_div_fixup_f32 v2, v8, v2, 1.0
	v_lshlrev_b64 v[4:5], 11, v[4:5]
	v_lshl_add_u64 v[4:5], v[6:7], 0, v[4:5]
	v_pk_mul_f32 v[6:7], v[56:57], v[2:3] op_sel_hi:[1,0]
	v_pk_mul_f32 v[8:9], v[58:59], v[2:3] op_sel_hi:[1,0]
	s_waitcnt lgkmcnt(0)
	v_add_f32_e32 v1, v1, v10
	v_cvt_pk_bf16_f32 v6, v6, v7
	v_cvt_pk_bf16_f32 v7, v8, v9
	v_div_scale_f32 v10, s[2:3], v1, v1, 1.0
	global_store_dwordx2 v[4:5], v[6:7], off offset:512
	v_pk_mul_f32 v[6:7], v[48:49], v[2:3] op_sel_hi:[1,0]
	v_pk_mul_f32 v[8:9], v[50:51], v[2:3] op_sel_hi:[1,0]
	v_rcp_f32_e32 v11, v10
	v_cvt_pk_bf16_f32 v6, v6, v7
	v_cvt_pk_bf16_f32 v7, v8, v9
	global_store_dwordx2 v[4:5], v[6:7], off offset:544
	v_pk_mul_f32 v[6:7], v[44:45], v[2:3] op_sel_hi:[1,0]
	v_pk_mul_f32 v[8:9], v[46:47], v[2:3] op_sel_hi:[1,0]
	v_cvt_pk_bf16_f32 v6, v6, v7
	v_cvt_pk_bf16_f32 v7, v8, v9
	global_store_dwordx2 v[4:5], v[6:7], off offset:576
	v_pk_mul_f32 v[6:7], v[52:53], v[2:3] op_sel_hi:[1,0]
	v_pk_mul_f32 v[8:9], v[54:55], v[2:3] op_sel_hi:[1,0]
	v_fma_f32 v2, -v10, v11, 1.0
	v_cvt_pk_bf16_f32 v6, v6, v7
	v_cvt_pk_bf16_f32 v7, v8, v9
	v_fmac_f32_e32 v11, v2, v11
	v_div_scale_f32 v2, vcc, 1.0, v1, 1.0
	global_store_dwordx2 v[4:5], v[6:7], off offset:608
	v_mul_f32_e32 v6, v2, v11
	v_fma_f32 v7, -v10, v6, v2
	v_fmac_f32_e32 v6, v7, v11
	v_fma_f32 v2, -v10, v6, v2
	v_div_fmas_f32 v2, v2, v11, v6
	v_div_fixup_f32 v2, v2, v1, 1.0
	s_mov_b32 s2, 0x8000
	v_pk_mul_f32 v[6:7], v[32:33], v[2:3] op_sel_hi:[1,0]
	v_pk_mul_f32 v[8:9], v[34:35], v[2:3] op_sel_hi:[1,0]
	v_add_co_u32_e32 v4, vcc, s2, v4
	v_cvt_pk_bf16_f32 v6, v6, v7
	v_cvt_pk_bf16_f32 v7, v8, v9
	v_addc_co_u32_e32 v5, vcc, 0, v5, vcc
	global_store_dwordx2 v[4:5], v[6:7], off offset:512
	v_pk_mul_f32 v[6:7], v[28:29], v[2:3] op_sel_hi:[1,0]
	v_pk_mul_f32 v[8:9], v[30:31], v[2:3] op_sel_hi:[1,0]
	v_cvt_pk_bf16_f32 v6, v6, v7
	v_cvt_pk_bf16_f32 v7, v8, v9
	global_store_dwordx2 v[4:5], v[6:7], off offset:544
	v_pk_mul_f32 v[6:7], v[36:37], v[2:3] op_sel_hi:[1,0]
	v_pk_mul_f32 v[8:9], v[38:39], v[2:3] op_sel_hi:[1,0]
	v_cvt_pk_bf16_f32 v6, v6, v7
	v_cvt_pk_bf16_f32 v7, v8, v9
	global_store_dwordx2 v[4:5], v[6:7], off offset:576
	v_pk_mul_f32 v[6:7], v[40:41], v[2:3] op_sel_hi:[1,0]
	v_pk_mul_f32 v[8:9], v[42:43], v[2:3] op_sel_hi:[1,0]
	v_cvt_pk_bf16_f32 v6, v6, v7
	v_cvt_pk_bf16_f32 v7, v8, v9
	v_readlane_b32 s41, v251, 59
	v_readlane_b32 s42, v251, 60
	v_readlane_b32 s43, v251, 61
	v_readlane_b32 s44, v251, 62
	v_readlane_b32 s45, v251, 63
	v_readlane_b32 s48, v252, 2
	v_readlane_b32 s49, v252, 3
	v_readlane_b32 s50, v252, 4
	v_readlane_b32 s51, v252, 5
	v_readlane_b32 s52, v252, 6
	v_readlane_b32 s53, v252, 7
	v_readlane_b32 s54, v252, 8
	v_readlane_b32 s55, v252, 9
	global_store_dwordx2 v[4:5], v[6:7], off offset:608

; DEVI float ex2(float x) { return __builtin_amdgcn_exp2f(x); }
; DEVI f32x4 mfma16(bf16x8 a, bf16x8 b, f32x4 c) { return __builtin_amdgcn_mfma_f32_16x16x32_bf16(a, b, c, 0, 0, 0); }
; template <int DK>
; DEVI void attn_tile(const char* kb, const char* vb, const bool first, const bf16x8 (&qf)[2][DK / 32], f32x4 (&o)[2][4],
;                     float (&mrun)[2], float (&lsum)[2], const int l15, const int quad) {
;     ...
;   f32x4 s[2][4];
; #pragma unroll
;   for (int qt = 0; qt < 2; ++qt)
; #pragma unroll
;     for (int ks = 0; ks < 4; ++ks) { const float nm = -mrun[qt]; s[qt][ks] = f32x4{nm, nm, nm, nm}; }
; #pragma unroll
;   for (int ks = 0; ks < 4; ++ks)
; #pragma unroll
;     for (int kk = 0; kk < NKK; ++kk) {
;       bf16x8 kf = *reinterpret_cast<const bf16x8*>(kb + (ks * 16 + l15) * KSTR + (kk * 32 + quad * 8) * 2);
;       s[0][ks] = mfma16(kf, qf[0][kk], s[0][ks]);
;       s[1][ks] = mfma16(kf, qf[1][kk], s[1][ks]);
;     }
;   bf16x8 pf[2][2];
; #pragma unroll
;   for (int qt = 0; qt < 2; ++qt) {
;     float mx = fmaxf(fmaxf(s[qt][0][0], s[qt][0][1]), fmaxf(s[qt][0][2], s[qt][0][3]));
; #pragma unroll
;     for (int ks = 1; ks < 4; ++ks) mx = fmaxf(mx, fmaxf(fmaxf(s[qt][ks][0], s[qt][ks][1]), fmaxf(s[qt][ks][2], s[qt][ks][3])));
;     if (__any(first || (mx > 8.f))) {
;       float rm = fmaxf(mx, __shfl_xor(mx, 16));
;       rm = fmaxf(rm, __shfl_xor(rm, 32));
;       const float delta = first ? rm : fmaxf(rm, 0.f);
;       const float alpha = first ? 1.f : ex2(-delta);
;       mrun[qt] += delta;
;       lsum[qt] *= alpha;
; #pragma unroll
;       for (int ks = 0; ks < 4; ++ks)
; #pragma unroll
;         for (int j = 0; j < 4; ++j) s[qt][ks][j] -= delta;
; #pragma unroll
;       for (int dd = 0; dd < 4; ++dd)
; #pragma unroll
;         for (int j = 0; j < 4; ++j) o[qt][dd][j] *= alpha;
;     }
.LBB0_1596:
	s_add_i32 s3, s2, 1
	s_min_i32 s4, s3, s1
	s_lshl_b32 s8, s4, 6
	v_add_u32_e32 v98, s8, v152
	v_add_u32_e32 v102, s8, v154
	v_ashrrev_i32_e32 v99, 31, v98
	v_ashrrev_i32_e32 v103, 31, v102
	s_lshl_b32 s4, s4, 7
	v_lshlrev_b64 v[98:99], 7, v[98:99]
	v_lshlrev_b64 v[102:103], 7, v[102:103]
	v_lshl_add_u64 v[110:111], v[158:159], 0, s[4:5]
	v_lshl_add_u64 v[98:99], v[166:167], 0, v[98:99]
	v_lshl_add_u64 v[102:103], v[168:169], 0, v[102:103]
	v_lshl_add_u64 v[106:107], v[110:111], 0, v[162:163]
	v_lshl_add_u64 v[110:111], v[110:111], 0, v[164:165]
	global_load_dwordx4 v[98:101], v[98:99], off
	s_bitcmp1_b32 s2, 0
	global_load_dwordx4 v[102:105], v[102:103], off
	s_cselect_b32 s4, 0x4c00, 0
	global_load_dwordx4 v[106:109], v[106:107], off
	v_add_u32_e32 v114, s4, v170
	global_load_dwordx4 v[110:113], v[110:111], off
	v_add_u32_e32 v214, v114, v150
	v_add_u32_e32 v114, s4, v190
	v_add_u32_e32 v206, v114, v150
	v_add_u32_e32 v114, s4, v191
	v_add_u32_e32 v199, v114, v150
	v_add_u32_e32 v114, s4, v192
	v_add_u32_e32 v198, v114, v150
	ds_read_b128 v[114:117], v214
	ds_read_b128 v[122:125], v214 offset:64
	v_xor_b32_e32 v138, 0x80000000, v161
	v_mov_b32_e32 v139, v138
	v_mov_b32_e32 v140, v138
	v_mov_b32_e32 v141, v138
	v_xor_b32_e32 v142, 0x80000000, v157
	v_mov_b32_e32 v143, v142
	s_waitcnt lgkmcnt(1)
	v_mfma_f32_16x16x32_bf16 v[118:121], v[114:117], v[2:5], v[138:141]
	v_mov_b32_e32 v144, v142
	v_mov_b32_e32 v145, v142
	ds_read_b128 v[134:137], v206 offset:64
	s_waitcnt lgkmcnt(1)
	v_mfma_f32_16x16x32_bf16 v[126:129], v[122:125], v[10:13], v[118:121]
	ds_read_b128 v[200:203], v199 offset:64
	ds_read_b128 v[208:211], v198 offset:64
	s_nop 0
	ds_read_b128 v[118:121], v206
	v_mfma_f32_16x16x32_bf16 v[114:117], v[114:117], v[6:9], v[142:145]
	v_mfma_f32_16x16x32_bf16 v[114:117], v[122:125], v[14:17], v[114:117]
	s_waitcnt lgkmcnt(0)
	v_mfma_f32_16x16x32_bf16 v[122:125], v[118:121], v[2:5], v[138:141]
	v_mfma_f32_16x16x32_bf16 v[118:121], v[118:121], v[6:9], v[142:145]
	v_mfma_f32_16x16x32_bf16 v[130:133], v[134:137], v[10:13], v[122:125]
	v_mfma_f32_16x16x32_bf16 v[122:125], v[134:137], v[14:17], v[118:121]
	s_nop 5
	ds_read_b128 v[118:121], v199
	s_waitcnt lgkmcnt(0)
	v_mfma_f32_16x16x32_bf16 v[134:137], v[118:121], v[2:5], v[138:141]
	v_mfma_f32_16x16x32_bf16 v[118:121], v[118:121], v[6:9], v[142:145]
	v_mfma_f32_16x16x32_bf16 v[134:137], v[200:203], v[10:13], v[134:137]
	v_mfma_f32_16x16x32_bf16 v[118:121], v[200:203], v[14:17], v[118:121]
	ds_read_b128 v[200:203], v198
	s_waitcnt lgkmcnt(0)
	v_mfma_f32_16x16x32_bf16 v[138:141], v[200:203], v[2:5], v[138:141]
	v_mfma_f32_16x16x32_bf16 v[200:203], v[200:203], v[6:9], v[142:145]
	v_mfma_f32_16x16x32_bf16 v[142:145], v[208:211], v[10:13], v[138:141]
	v_mfma_f32_16x16x32_bf16 v[138:141], v[208:211], v[14:17], v[200:203]
	s_nop 5
	v_max3_f32 v200, v127, v126, v129
	v_max3_f32 v201, v128, v133, v132
	v_max3_f32 v202, v137, v136, v145
	v_max3_f32 v203, v144, v130, v131
	v_max3_f32 v200, v200, v201, v134
	v_max3_f32 v202, v202, v203, v135
	v_max3_f32 v200, v200, v202, v142
	v_max_f32_e32 v200, v200, v143
	v_cmp_lt_f32_e32 vcc, s19, v200
	s_cbranch_vccz .LBB0_1598
	v_cmp_lt_i32_e32 vcc, v181, v182
	s_nop 1
	v_cndmask_b32_e32 v201, v180, v181, vcc
	v_lshlrev_b32_e32 v201, 2, v201
	ds_bpermute_b32 v201, v201, v200
	v_max_f32_e32 v200, v200, v200
	v_cmp_lt_i32_e32 vcc, v183, v182
	s_waitcnt lgkmcnt(0)
	v_max_f32_e32 v201, v201, v201
	v_max_f32_e32 v200, v200, v201
	v_cndmask_b32_e32 v201, v180, v183, vcc
	v_lshlrev_b32_e32 v201, 2, v201
	ds_bpermute_b32 v201, v201, v200
	s_waitcnt lgkmcnt(0)
	v_max3_f32 v200, v200, v201, 0
	v_exp_f32_e64 v202, -v200
	v_add_f32_e32 v161, v161, v200
	v_pk_add_f32 v[126:127], v[126:127], v[200:201] op_sel_hi:[1,0] neg_lo:[0,1] neg_hi:[0,1]
	v_pk_add_f32 v[128:129], v[128:129], v[200:201] op_sel_hi:[1,0] neg_lo:[0,1] neg_hi:[0,1]
	v_mul_f32_e32 v175, v175, v202
	v_pk_add_f32 v[130:131], v[130:131], v[200:201] op_sel_hi:[1,0] neg_lo:[0,1] neg_hi:[0,1]
	v_pk_add_f32 v[132:133], v[132:133], v[200:201] op_sel_hi:[1,0] neg_lo:[0,1] neg_hi:[0,1]
	v_pk_add_f32 v[134:135], v[134:135], v[200:201] op_sel_hi:[1,0] neg_lo:[0,1] neg_hi:[0,1]
	v_pk_add_f32 v[136:137], v[136:137], v[200:201] op_sel_hi:[1,0] neg_lo:[0,1] neg_hi:[0,1]
	v_pk_add_f32 v[142:143], v[142:143], v[200:201] op_sel_hi:[1,0] neg_lo:[0,1] neg_hi:[0,1]
	v_pk_add_f32 v[144:145], v[144:145], v[200:201] op_sel_hi:[1,0] neg_lo:[0,1] neg_hi:[0,1]
	v_pk_mul_f32 v[52:53], v[52:53], v[202:203] op_sel_hi:[1,0]
	v_pk_mul_f32 v[50:51], v[50:51], v[202:203] op_sel_hi:[1,0]
	v_pk_mul_f32 v[56:57], v[56:57], v[202:203] op_sel_hi:[1,0]
	v_pk_mul_f32 v[54:55], v[54:55], v[202:203] op_sel_hi:[1,0]
	v_pk_mul_f32 v[60:61], v[60:61], v[202:203] op_sel_hi:[1,0]
	v_pk_mul_f32 v[58:59], v[58:59], v[202:203] op_sel_hi:[1,0]
	v_pk_mul_f32 v[64:65], v[64:65], v[202:203] op_sel_hi:[1,0]
	v_pk_mul_f32 v[62:63], v[62:63], v[202:203] op_sel_hi:[1,0]
; DEVI float ex2(float x) { return __builtin_amdgcn_exp2f(x); }
; template <int DK>
; DEVI void attn_tile(const char* kb, const char* vb, const bool first, const bf16x8 (&qf)[2][DK / 32], f32x4 (&o)[2][4],
;                     float (&mrun)[2], float (&lsum)[2], const int l15, const int quad) {
;     ...
;     float mx = fmaxf(fmaxf(s[qt][0][0], s[qt][0][1]), fmaxf(s[qt][0][2], s[qt][0][3]));
; #pragma unroll
;     for (int ks = 1; ks < 4; ++ks) mx = fmaxf(mx, fmaxf(fmaxf(s[qt][ks][0], s[qt][ks][1]), fmaxf(s[qt][ks][2], s[qt][ks][3])));
;     if (__any(first || (mx > 8.f))) {
;       float rm = fmaxf(mx, __shfl_xor(mx, 16));
;       rm = fmaxf(rm, __shfl_xor(rm, 32));
;       const float delta = first ? rm : fmaxf(rm, 0.f);
;       const float alpha = first ? 1.f : ex2(-delta);
;       mrun[qt] += delta;
;       lsum[qt] *= alpha;
; #pragma unroll
;       for (int ks = 0; ks < 4; ++ks)
; #pragma unroll
;         for (int j = 0; j < 4; ++j) s[qt][ks][j] -= delta;
; #pragma unroll
;       for (int dd = 0; dd < 4; ++dd)
; #pragma unroll
;         for (int j = 0; j < 4; ++j) o[qt][dd][j] *= alpha;
;     }
.LBB0_1598:
	v_max3_f32 v200, v115, v114, v117
	v_max3_f32 v201, v116, v125, v124
	v_max3_f32 v202, v121, v120, v141
	v_max3_f32 v203, v140, v122, v123
	v_max3_f32 v200, v200, v201, v118
	v_max3_f32 v202, v202, v203, v119
	v_max3_f32 v200, v200, v202, v138
	v_max_f32_e32 v200, v200, v139
	v_cmp_lt_f32_e32 vcc, s19, v200
	s_cbranch_vccz .LBB0_1600
	v_cmp_lt_i32_e32 vcc, v181, v182
	s_nop 1
	v_cndmask_b32_e32 v201, v180, v181, vcc
	v_lshlrev_b32_e32 v201, 2, v201
	ds_bpermute_b32 v201, v201, v200
	v_max_f32_e32 v200, v200, v200
	v_cmp_lt_i32_e32 vcc, v183, v182
	s_waitcnt lgkmcnt(0)
	v_max_f32_e32 v201, v201, v201
	v_max_f32_e32 v200, v200, v201
	v_cndmask_b32_e32 v201, v180, v183, vcc
	v_lshlrev_b32_e32 v201, 2, v201
	ds_bpermute_b32 v201, v201, v200
	s_waitcnt lgkmcnt(0)
	v_max3_f32 v200, v200, v201, 0
	v_exp_f32_e64 v202, -v200
	v_add_f32_e32 v157, v157, v200
	v_pk_add_f32 v[114:115], v[114:115], v[200:201] op_sel_hi:[1,0] neg_lo:[0,1] neg_hi:[0,1]
	v_pk_add_f32 v[116:117], v[116:117], v[200:201] op_sel_hi:[1,0] neg_lo:[0,1] neg_hi:[0,1]
	v_mul_f32_e32 v174, v174, v202
	v_pk_add_f32 v[122:123], v[122:123], v[200:201] op_sel_hi:[1,0] neg_lo:[0,1] neg_hi:[0,1]
	v_pk_add_f32 v[124:125], v[124:125], v[200:201] op_sel_hi:[1,0] neg_lo:[0,1] neg_hi:[0,1]
	v_pk_add_f32 v[118:119], v[118:119], v[200:201] op_sel_hi:[1,0] neg_lo:[0,1] neg_hi:[0,1]
	v_pk_add_f32 v[120:121], v[120:121], v[200:201] op_sel_hi:[1,0] neg_lo:[0,1] neg_hi:[0,1]
	v_pk_add_f32 v[138:139], v[138:139], v[200:201] op_sel_hi:[1,0] neg_lo:[0,1] neg_hi:[0,1]
	v_pk_add_f32 v[140:141], v[140:141], v[200:201] op_sel_hi:[1,0] neg_lo:[0,1] neg_hi:[0,1]
	v_pk_mul_f32 v[36:37], v[36:37], v[202:203] op_sel_hi:[1,0]
	v_pk_mul_f32 v[34:35], v[34:35], v[202:203] op_sel_hi:[1,0]
	v_pk_mul_f32 v[40:41], v[40:41], v[202:203] op_sel_hi:[1,0]
	v_pk_mul_f32 v[38:39], v[38:39], v[202:203] op_sel_hi:[1,0]
	v_pk_mul_f32 v[44:45], v[44:45], v[202:203] op_sel_hi:[1,0]
	v_pk_mul_f32 v[42:43], v[42:43], v[202:203] op_sel_hi:[1,0]
	v_pk_mul_f32 v[48:49], v[48:49], v[202:203] op_sel_hi:[1,0]
	v_pk_mul_f32 v[46:47], v[46:47], v[202:203] op_sel_hi:[1,0]

; DEVI float ex2(float x) { return __builtin_amdgcn_exp2f(x); }
; template <int DK>
; DEVI void attn_tile(const char* kb, const char* vb, const bool first, const bf16x8 (&qf)[2][DK / 32], f32x4 (&o)[2][4],
;                     float (&mrun)[2], float (&lsum)[2], const int l15, const int quad) {
;     ...
;     float mx = fmaxf(fmaxf(s[qt][0][0], s[qt][0][1]), fmaxf(s[qt][0][2], s[qt][0][3]));
; #pragma unroll
;     for (int ks = 1; ks < 4; ++ks) mx = fmaxf(mx, fmaxf(fmaxf(s[qt][ks][0], s[qt][ks][1]), fmaxf(s[qt][ks][2], s[qt][ks][3])));
;     if (__any(first || (mx > 8.f))) {
;       float rm = fmaxf(mx, __shfl_xor(mx, 16));
;       rm = fmaxf(rm, __shfl_xor(rm, 32));
;       const float delta = first ? rm : fmaxf(rm, 0.f);
;       const float alpha = first ? 1.f : ex2(-delta);
;       mrun[qt] += delta;
;       lsum[qt] *= alpha;
; #pragma unroll
;       for (int ks = 0; ks < 4; ++ks)
; #pragma unroll
;         for (int j = 0; j < 4; ++j) s[qt][ks][j] -= delta;
; #pragma unroll
;       for (int dd = 0; dd < 4; ++dd)
; #pragma unroll
;         for (int j = 0; j < 4; ++j) o[qt][dd][j] *= alpha;
;     }
.LBB0_1602:
	v_max3_f32 v198, v123, v122, v125
	v_max3_f32 v199, v124, v129, v128
	v_max3_f32 v206, v117, v116, v121
	v_max3_f32 v214, v120, v126, v127
	v_max3_f32 v198, v198, v199, v114
	v_max3_f32 v206, v206, v214, v115
	v_max3_f32 v198, v198, v206, v118
	v_max_f32_e32 v198, v198, v119
	v_cmp_lt_f32_e32 vcc, s19, v198
	s_cbranch_vccz .LBB0_1604
	v_cmp_lt_i32_e32 vcc, v181, v182
	s_nop 1
	v_cndmask_b32_e32 v199, v180, v181, vcc
	v_lshlrev_b32_e32 v199, 2, v199
	ds_bpermute_b32 v199, v199, v198
	v_max_f32_e32 v198, v198, v198
	v_cmp_lt_i32_e32 vcc, v183, v182
	s_waitcnt lgkmcnt(0)
	v_max_f32_e32 v199, v199, v199
	v_max_f32_e32 v198, v198, v199
	v_cndmask_b32_e32 v199, v180, v183, vcc
	v_lshlrev_b32_e32 v199, 2, v199
	ds_bpermute_b32 v199, v199, v198
	s_waitcnt lgkmcnt(0)
	v_max3_f32 v198, v198, v199, 0
	v_exp_f32_e64 v206, -v198
	v_add_f32_e32 v172, v172, v198
	v_pk_add_f32 v[122:123], v[122:123], v[198:199] op_sel_hi:[1,0] neg_lo:[0,1] neg_hi:[0,1]
	v_pk_add_f32 v[124:125], v[124:125], v[198:199] op_sel_hi:[1,0] neg_lo:[0,1] neg_hi:[0,1]
	v_mul_f32_e32 v197, v197, v206
	v_pk_add_f32 v[126:127], v[126:127], v[198:199] op_sel_hi:[1,0] neg_lo:[0,1] neg_hi:[0,1]
	v_pk_add_f32 v[128:129], v[128:129], v[198:199] op_sel_hi:[1,0] neg_lo:[0,1] neg_hi:[0,1]
	v_pk_add_f32 v[114:115], v[114:115], v[198:199] op_sel_hi:[1,0] neg_lo:[0,1] neg_hi:[0,1]
	v_pk_add_f32 v[116:117], v[116:117], v[198:199] op_sel_hi:[1,0] neg_lo:[0,1] neg_hi:[0,1]
	v_pk_add_f32 v[118:119], v[118:119], v[198:199] op_sel_hi:[1,0] neg_lo:[0,1] neg_hi:[0,1]
	v_pk_add_f32 v[120:121], v[120:121], v[198:199] op_sel_hi:[1,0] neg_lo:[0,1] neg_hi:[0,1]
	v_pk_mul_f32 v[68:69], v[68:69], v[206:207] op_sel_hi:[1,0]
	v_pk_mul_f32 v[66:67], v[66:67], v[206:207] op_sel_hi:[1,0]
	v_pk_mul_f32 v[76:77], v[76:77], v[206:207] op_sel_hi:[1,0]
	v_pk_mul_f32 v[74:75], v[74:75], v[206:207] op_sel_hi:[1,0]
	v_pk_mul_f32 v[84:85], v[84:85], v[206:207] op_sel_hi:[1,0]
	v_pk_mul_f32 v[82:83], v[82:83], v[206:207] op_sel_hi:[1,0]
	v_pk_mul_f32 v[92:93], v[92:93], v[206:207] op_sel_hi:[1,0]
	v_pk_mul_f32 v[90:91], v[90:91], v[206:207] op_sel_hi:[1,0]

; DEVI float ex2(float x) { return __builtin_amdgcn_exp2f(x); }
; DEVI f32x4 mfma16(bf16x8 a, bf16x8 b, f32x4 c) { return __builtin_amdgcn_mfma_f32_16x16x32_bf16(a, b, c, 0, 0, 0); }
; template <int DK>
; DEVI void attn_tile(const char* kb, const char* vb, const bool first, const bf16x8 (&qf)[2][DK / 32], f32x4 (&o)[2][4],
;                     float (&mrun)[2], float (&lsum)[2], const int l15, const int quad) {
;     ...
;   f32x4 s[2][4];
; #pragma unroll
;   for (int qt = 0; qt < 2; ++qt)
; #pragma unroll
;     for (int ks = 0; ks < 4; ++ks) { const float nm = -mrun[qt]; s[qt][ks] = f32x4{nm, nm, nm, nm}; }
; #pragma unroll
;   for (int ks = 0; ks < 4; ++ks)
; #pragma unroll
;     for (int kk = 0; kk < NKK; ++kk) {
;       bf16x8 kf = *reinterpret_cast<const bf16x8*>(kb + (ks * 16 + l15) * KSTR + (kk * 32 + quad * 8) * 2);
;       s[0][ks] = mfma16(kf, qf[0][kk], s[0][ks]);
;       s[1][ks] = mfma16(kf, qf[1][kk], s[1][ks]);
;     }
;   bf16x8 pf[2][2];
; #pragma unroll
;   for (int qt = 0; qt < 2; ++qt) {
;     float mx = fmaxf(fmaxf(s[qt][0][0], s[qt][0][1]), fmaxf(s[qt][0][2], s[qt][0][3]));
; #pragma unroll
;     for (int ks = 1; ks < 4; ++ks) mx = fmaxf(mx, fmaxf(fmaxf(s[qt][ks][0], s[qt][ks][1]), fmaxf(s[qt][ks][2], s[qt][ks][3])));
;     if (__any(first || (mx > 8.f))) {
;       float rm = fmaxf(mx, __shfl_xor(mx, 16));
;       rm = fmaxf(rm, __shfl_xor(rm, 32));
;       const float delta = first ? rm : fmaxf(rm, 0.f);
;       const float alpha = first ? 1.f : ex2(-delta);
;       mrun[qt] += delta;
;       lsum[qt] *= alpha;
; #pragma unroll
;       for (int ks = 0; ks < 4; ++ks)
; #pragma unroll
;         for (int j = 0; j < 4; ++j) s[qt][ks][j] -= delta;
; #pragma unroll
;       for (int dd = 0; dd < 4; ++dd)
; #pragma unroll
;         for (int j = 0; j < 4; ++j) o[qt][dd][j] *= alpha;
;     }
.LBB0_1618:
	s_add_i32 s3, s2, 1
	s_min_i32 s4, s3, s1
	s_lshl_b32 s16, s4, 6
	s_lshl_b32 s4, s4, 7
	v_add_u32_e32 v58, s16, v153
	v_add_u32_e32 v62, s16, v155
	v_add_u32_e32 v66, s16, v161
	v_lshl_add_u64 v[74:75], v[158:159], 0, s[4:5]
	v_mad_i64_i32 v[58:59], s[6:7], v58, s23, v[170:171]
	v_mad_i64_i32 v[62:63], s[6:7], v62, s23, v[172:173]
	v_mad_i64_i32 v[66:67], s[6:7], v66, s23, v[174:175]
	v_lshl_add_u64 v[70:71], v[74:75], 0, v[166:167]
	v_lshl_add_u64 v[74:75], v[74:75], 0, v[168:169]
	global_load_dwordx4 v[58:61], v[58:59], off
	s_bitcmp1_b32 s2, 0
	global_load_dwordx4 v[62:65], v[62:63], off
	s_cselect_b32 s4, 0x5c00, 0
	global_load_dwordx4 v[66:69], v[66:67], off
	v_add3_u32 v78, s4, v195, v150
	global_load_dwordx4 v[70:73], v[70:71], off
	v_xor_b32_e32 v212, 0x80000000, v162
	global_load_dwordx4 v[74:77], v[74:75], off
	ds_read_b128 v[110:113], v78
	ds_read_b128 v[126:129], v78 offset:64
	ds_read_b128 v[204:207], v78 offset:128
	v_xor_b32_e32 v216, 0x80000000, v1
	v_mov_b32_e32 v213, v212
	v_mov_b32_e32 v214, v212
	v_mov_b32_e32 v215, v212
	v_mov_b32_e32 v217, v216
	v_mov_b32_e32 v218, v216
	v_mov_b32_e32 v219, v216
	s_waitcnt lgkmcnt(2)
	v_mfma_f32_16x16x32_bf16 v[220:223], v[110:113], v[2:5], v[212:215]
	v_add3_u32 v78, s4, v196, v150
	ds_read_b128 v[208:211], v78
	ds_read_b128 v[130:133], v78 offset:64
	ds_read_b128 v[114:117], v78 offset:128
	v_add3_u32 v78, s4, v197, v150
	v_mfma_f32_16x16x32_bf16 v[110:113], v[110:113], v[6:9], v[216:219]
	ds_read_b128 v[146:149], v78
	ds_read_b128 v[142:145], v78 offset:64
	ds_read_b128 v[118:121], v78 offset:128
	v_add3_u32 v78, s4, v198, v150
	ds_read_b128 v[138:141], v78
	ds_read_b128 v[134:137], v78 offset:64
	ds_read_b128 v[122:125], v78 offset:128
	s_waitcnt lgkmcnt(10)
	v_mfma_f32_16x16x32_bf16 v[220:223], v[126:129], v[10:13], v[220:223]
	v_add3_u32 v78, s4, v199, v160
	v_add_u32_e32 v78, 0x3800, v78
	ds_read2_b64 v[106:109], v78 offset1:4
	ds_read2_b64 v[94:97], v78 offset0:8 offset1:12
	v_mfma_f32_16x16x32_bf16 v[110:113], v[126:129], v[14:17], v[110:113]
	v_add3_u32 v78, s4, v200, v160
	v_add_u32_e32 v78, 0x3800, v78
	ds_read2_b64 v[102:105], v78 offset1:4
	ds_read2_b64 v[90:93], v78 offset0:8 offset1:12
	s_waitcnt lgkmcnt(13)
	v_mfma_f32_16x16x32_bf16 v[126:129], v[204:207], v[18:21], v[220:223]
	v_add3_u32 v78, s4, v201, v160
	v_add_u32_e32 v78, 0x3800, v78
	ds_read2_b64 v[98:101], v78 offset1:4
	ds_read2_b64 v[86:89], v78 offset0:8 offset1:12
	v_mfma_f32_16x16x32_bf16 v[110:113], v[204:207], v[22:25], v[110:113]
	v_add3_u32 v78, s4, v202, v160
	v_add_u32_e32 v78, 0x3800, v78
	ds_read2_b64 v[82:85], v78 offset1:4
	ds_read2_b64 v[78:81], v78 offset0:8 offset1:12
	s_waitcnt lgkmcnt(14)
	v_mfma_f32_16x16x32_bf16 v[204:207], v[208:211], v[2:5], v[212:215]
	v_mfma_f32_16x16x32_bf16 v[208:211], v[208:211], v[6:9], v[216:219]
	v_mfma_f32_16x16x32_bf16 v[204:207], v[130:133], v[10:13], v[204:207]
	v_mfma_f32_16x16x32_bf16 v[208:211], v[130:133], v[14:17], v[208:211]
	v_mfma_f32_16x16x32_bf16 v[130:133], v[114:117], v[18:21], v[204:207]
	s_waitcnt lgkmcnt(13)
	v_mfma_f32_16x16x32_bf16 v[204:207], v[146:149], v[2:5], v[212:215]
	v_mfma_f32_16x16x32_bf16 v[146:149], v[146:149], v[6:9], v[216:219]
	s_waitcnt lgkmcnt(12)
	v_mfma_f32_16x16x32_bf16 v[204:207], v[142:145], v[10:13], v[204:207]
	v_mfma_f32_16x16x32_bf16 v[146:149], v[142:145], v[14:17], v[146:149]
	s_waitcnt lgkmcnt(11)
	v_mfma_f32_16x16x32_bf16 v[142:145], v[118:121], v[18:21], v[204:207]
	v_mfma_f32_16x16x32_bf16 v[118:121], v[118:121], v[22:25], v[146:149]
	s_waitcnt lgkmcnt(10)
	v_mfma_f32_16x16x32_bf16 v[146:149], v[138:141], v[2:5], v[212:215]
	v_mfma_f32_16x16x32_bf16 v[138:141], v[138:141], v[6:9], v[216:219]
	s_waitcnt lgkmcnt(9)
	v_mfma_f32_16x16x32_bf16 v[146:149], v[134:137], v[10:13], v[146:149]
	v_mfma_f32_16x16x32_bf16 v[138:141], v[134:137], v[14:17], v[138:141]
	s_waitcnt lgkmcnt(8)
	v_mfma_f32_16x16x32_bf16 v[134:137], v[122:125], v[18:21], v[146:149]
	v_mfma_f32_16x16x32_bf16 v[122:125], v[122:125], v[22:25], v[138:141]
	s_nop 4
	v_mfma_f32_16x16x32_bf16 v[114:117], v[114:117], v[22:25], v[208:211]
	v_max3_f32 v138, v127, v126, v129
	v_max3_f32 v139, v128, v133, v132
	v_max3_f32 v140, v145, v144, v137
	v_max3_f32 v141, v136, v130, v131
	v_max3_f32 v138, v138, v139, v142
	v_max3_f32 v140, v140, v141, v143
	v_max3_f32 v138, v138, v140, v134
	v_max_f32_e32 v138, v138, v135
	v_cmp_lt_f32_e32 vcc, s19, v138
	s_cbranch_vccz .LBB0_1620
	v_cmp_lt_i32_e32 vcc, v181, v182
	s_nop 1
	v_cndmask_b32_e32 v139, v180, v181, vcc
	v_lshlrev_b32_e32 v139, 2, v139
	ds_bpermute_b32 v139, v139, v138
	v_max_f32_e32 v138, v138, v138
	v_cmp_lt_i32_e32 vcc, v183, v182
	s_waitcnt lgkmcnt(0)
	v_max_f32_e32 v139, v139, v139
	v_max_f32_e32 v138, v138, v139
	v_cndmask_b32_e32 v139, v180, v183, vcc
	v_lshlrev_b32_e32 v139, 2, v139
	ds_bpermute_b32 v139, v139, v138
	s_waitcnt lgkmcnt(0)
	v_max3_f32 v138, v138, v139, 0
	v_exp_f32_e64 v140, -v138
	v_add_f32_e32 v162, v162, v138
	v_pk_add_f32 v[126:127], v[126:127], v[138:139] op_sel_hi:[1,0] neg_lo:[0,1] neg_hi:[0,1]
	v_pk_add_f32 v[128:129], v[128:129], v[138:139] op_sel_hi:[1,0] neg_lo:[0,1] neg_hi:[0,1]
	v_mul_f32_e32 v164, v164, v140
	v_pk_add_f32 v[130:131], v[130:131], v[138:139] op_sel_hi:[1,0] neg_lo:[0,1] neg_hi:[0,1]
	v_pk_add_f32 v[132:133], v[132:133], v[138:139] op_sel_hi:[1,0] neg_lo:[0,1] neg_hi:[0,1]
	v_pk_add_f32 v[142:143], v[142:143], v[138:139] op_sel_hi:[1,0] neg_lo:[0,1] neg_hi:[0,1]
	v_pk_add_f32 v[144:145], v[144:145], v[138:139] op_sel_hi:[1,0] neg_lo:[0,1] neg_hi:[0,1]
	v_pk_add_f32 v[134:135], v[134:135], v[138:139] op_sel_hi:[1,0] neg_lo:[0,1] neg_hi:[0,1]
	v_pk_add_f32 v[136:137], v[136:137], v[138:139] op_sel_hi:[1,0] neg_lo:[0,1] neg_hi:[0,1]
	v_pk_mul_f32 v[56:57], v[56:57], v[140:141] op_sel_hi:[1,0]
	v_pk_mul_f32 v[54:55], v[54:55], v[140:141] op_sel_hi:[1,0]
	v_pk_mul_f32 v[52:53], v[52:53], v[140:141] op_sel_hi:[1,0]
	v_pk_mul_f32 v[50:51], v[50:51], v[140:141] op_sel_hi:[1,0]
	v_pk_mul_f32 v[44:45], v[44:45], v[140:141] op_sel_hi:[1,0]
	v_pk_mul_f32 v[42:43], v[42:43], v[140:141] op_sel_hi:[1,0]
	v_pk_mul_f32 v[48:49], v[48:49], v[140:141] op_sel_hi:[1,0]
	v_pk_mul_f32 v[46:47], v[46:47], v[140:141] op_sel_hi:[1,0]
; DEVI float ex2(float x) { return __builtin_amdgcn_exp2f(x); }
; template <int DK>
; DEVI void attn_tile(const char* kb, const char* vb, const bool first, const bf16x8 (&qf)[2][DK / 32], f32x4 (&o)[2][4],
;                     float (&mrun)[2], float (&lsum)[2], const int l15, const int quad) {
;     ...
;     float mx = fmaxf(fmaxf(s[qt][0][0], s[qt][0][1]), fmaxf(s[qt][0][2], s[qt][0][3]));
; #pragma unroll
;     for (int ks = 1; ks < 4; ++ks) mx = fmaxf(mx, fmaxf(fmaxf(s[qt][ks][0], s[qt][ks][1]), fmaxf(s[qt][ks][2], s[qt][ks][3])));
;     if (__any(first || (mx > 8.f))) {
;       float rm = fmaxf(mx, __shfl_xor(mx, 16));
;       rm = fmaxf(rm, __shfl_xor(rm, 32));
;       const float delta = first ? rm : fmaxf(rm, 0.f);
;       const float alpha = first ? 1.f : ex2(-delta);
;       mrun[qt] += delta;
;       lsum[qt] *= alpha;
; #pragma unroll
;       for (int ks = 0; ks < 4; ++ks)
; #pragma unroll
;         for (int j = 0; j < 4; ++j) s[qt][ks][j] -= delta;
; #pragma unroll
;       for (int dd = 0; dd < 4; ++dd)
; #pragma unroll
;         for (int j = 0; j < 4; ++j) o[qt][dd][j] *= alpha;
;     }
;     float ps = 0.f;
; #pragma unroll
;     for (int ks = 0; ks < 4; ++ks)
; #pragma unroll
;       for (int j = 0; j < 4; ++j) { float pv = ex2(s[qt][ks][j]); s[qt][ks][j] = pv; ps += pv; }
;     lsum[qt] += ps;
.LBB0_1620:
	v_exp_f32_e32 v126, v126
	v_exp_f32_e32 v127, v127
	v_exp_f32_e32 v128, v128
	v_exp_f32_e32 v129, v129
	v_add_f32_e32 v138, 0, v126
	v_exp_f32_e32 v130, v130
	v_add_f32_e32 v138, v127, v138
	v_exp_f32_e32 v131, v131
	v_add_f32_e32 v138, v128, v138
	v_exp_f32_e32 v132, v132
	v_add_f32_e32 v138, v129, v138
	v_exp_f32_e32 v133, v133
	v_add_f32_e32 v138, v130, v138
	v_add_f32_e32 v138, v131, v138
	v_add_f32_e32 v138, v132, v138
	v_add_f32_e32 v146, v133, v138
	v_exp_f32_e32 v138, v142
	v_exp_f32_e32 v139, v143
	v_exp_f32_e32 v140, v144
	v_exp_f32_e32 v141, v145
	v_add_f32_e32 v142, v138, v146
	v_exp_f32_e32 v134, v134
	v_add_f32_e32 v142, v139, v142
	v_exp_f32_e32 v135, v135
	v_add_f32_e32 v142, v140, v142
	v_exp_f32_e32 v136, v136
	v_add_f32_e32 v142, v141, v142
	v_exp_f32_e32 v137, v137
	v_add_f32_e32 v142, v134, v142
	v_add_f32_e32 v142, v135, v142
	v_add_f32_e32 v142, v136, v142
	v_add_f32_e32 v142, v137, v142
	v_add_f32_e32 v164, v164, v142
	v_max3_f32 v142, v111, v110, v113
	v_max3_f32 v143, v112, v117, v116
	v_max3_f32 v144, v121, v120, v125
	v_max3_f32 v145, v124, v114, v115
	v_max3_f32 v142, v142, v143, v118
	v_max3_f32 v144, v144, v145, v119
	v_max3_f32 v142, v142, v144, v122
	v_max_f32_e32 v142, v142, v123
	v_cmp_lt_f32_e32 vcc, s19, v142
	s_cbranch_vccz .LBB0_1622
	v_cmp_lt_i32_e32 vcc, v181, v182
	s_nop 1
	v_cndmask_b32_e32 v143, v180, v181, vcc
	v_lshlrev_b32_e32 v143, 2, v143
	ds_bpermute_b32 v143, v143, v142
	v_max_f32_e32 v142, v142, v142
	v_cmp_lt_i32_e32 vcc, v183, v182
	s_waitcnt lgkmcnt(0)
	v_max_f32_e32 v143, v143, v143
	v_max_f32_e32 v142, v142, v143
	v_cndmask_b32_e32 v143, v180, v183, vcc
	v_lshlrev_b32_e32 v143, 2, v143
	ds_bpermute_b32 v143, v143, v142
	s_waitcnt lgkmcnt(0)
	v_max3_f32 v142, v142, v143, 0
	v_exp_f32_e64 v144, -v142
	v_add_f32_e32 v1, v1, v142
	v_pk_add_f32 v[110:111], v[110:111], v[142:143] op_sel_hi:[1,0] neg_lo:[0,1] neg_hi:[0,1]
	v_pk_add_f32 v[112:113], v[112:113], v[142:143] op_sel_hi:[1,0] neg_lo:[0,1] neg_hi:[0,1]
	v_mul_f32_e32 v157, v157, v144
	v_pk_add_f32 v[114:115], v[114:115], v[142:143] op_sel_hi:[1,0] neg_lo:[0,1] neg_hi:[0,1]
	v_pk_add_f32 v[116:117], v[116:117], v[142:143] op_sel_hi:[1,0] neg_lo:[0,1] neg_hi:[0,1]
	v_pk_add_f32 v[118:119], v[118:119], v[142:143] op_sel_hi:[1,0] neg_lo:[0,1] neg_hi:[0,1]
	v_pk_add_f32 v[120:121], v[120:121], v[142:143] op_sel_hi:[1,0] neg_lo:[0,1] neg_hi:[0,1]
	v_pk_add_f32 v[122:123], v[122:123], v[142:143] op_sel_hi:[1,0] neg_lo:[0,1] neg_hi:[0,1]
	v_pk_add_f32 v[124:125], v[124:125], v[142:143] op_sel_hi:[1,0] neg_lo:[0,1] neg_hi:[0,1]
	v_pk_mul_f32 v[36:37], v[36:37], v[144:145] op_sel_hi:[1,0]
	v_pk_mul_f32 v[34:35], v[34:35], v[144:145] op_sel_hi:[1,0]
	v_pk_mul_f32 v[28:29], v[28:29], v[144:145] op_sel_hi:[1,0]
	v_pk_mul_f32 v[26:27], v[26:27], v[144:145] op_sel_hi:[1,0]
	v_pk_mul_f32 v[32:33], v[32:33], v[144:145] op_sel_hi:[1,0]
	v_pk_mul_f32 v[30:31], v[30:31], v[144:145] op_sel_hi:[1,0]
	v_pk_mul_f32 v[40:41], v[40:41], v[144:145] op_sel_hi:[1,0]
	v_pk_mul_f32 v[38:39], v[38:39], v[144:145] op_sel_hi:[1,0]
